# GLA i-loop software-pipelined (v*k of step i+2 issued ahead of the state/output FMAs of steps i+1/i)
# baseline (speedup 1.0000x reference)
.Lgla2_loop:
	global_load_dword v110, v32, s[10:11]
	global_load_dword v111, v32, s[10:11] offset:-1024
	global_load_dword v112, v33, s[10:11]
	global_load_dword v113, v33, s[10:11] offset:-1024
	global_load_dword v114, v34, s[10:11]
	global_load_dword v116, v35, s[12:13]
	global_load_dword v117, v35, s[12:13] offset:4
	s_add_u32 s10, s10, 0x18000
	s_addc_u32 s11, s11, 0
	s_add_u32 s12, s12, 0x4000
	s_addc_u32 s13, s13, 0
	s_waitcnt lgkmcnt(4)
	v_pk_mul_f32 v[42:43], v[72:73], v[48:49] op_sel_hi:[1,0]
	v_pk_mul_f32 v[44:45], v[72:73], v[50:51] op_sel_hi:[1,0]
	v_pk_fma_f32 v[6:7], v[6:7], v[64:65], v[42:43] op_sel:[0,0,0] op_sel_hi:[1,0,1]
	s_waitcnt lgkmcnt(3)
	v_pk_mul_f32 v[42:43], v[72:73], v[52:53] op_sel_hi:[1,0]
	v_pk_fma_f32 v[8:9], v[8:9], v[64:65], v[44:45] op_sel:[0,1,0] op_sel_hi:[1,1,1]
	v_pk_mul_f32 v[44:45], v[72:73], v[54:55] op_sel_hi:[1,0]
	v_pk_mul_f32 v[38:39], v[6:7], v[48:49] op_sel:[0,1] op_sel_hi:[1,1]
	v_pk_fma_f32 v[10:11], v[10:11], v[66:67], v[42:43] op_sel:[0,0,0] op_sel_hi:[1,0,1]
	s_waitcnt lgkmcnt(1)
	v_pk_mul_f32 v[42:43], v[72:73], v[56:57] op_sel_hi:[1,0]
	v_pk_fma_f32 v[38:39], v[8:9], v[50:51], v[38:39] op_sel:[0,1,0] op_sel_hi:[1,1,1]
	v_pk_fma_f32 v[12:13], v[12:13], v[66:67], v[44:45] op_sel:[0,1,0] op_sel_hi:[1,1,1]
	v_pk_mul_f32 v[44:45], v[72:73], v[58:59] op_sel_hi:[1,0]
	v_pk_fma_f32 v[38:39], v[10:11], v[52:53], v[38:39] op_sel:[0,1,0] op_sel_hi:[1,1,1]
	v_pk_fma_f32 v[14:15], v[14:15], v[68:69], v[42:43] op_sel:[0,0,0] op_sel_hi:[1,0,1]
	s_waitcnt lgkmcnt(0)
	v_pk_mul_f32 v[42:43], v[72:73], v[60:61] op_sel_hi:[1,0]
	v_pk_fma_f32 v[38:39], v[12:13], v[54:55], v[38:39] op_sel:[0,1,0] op_sel_hi:[1,1,1]
	v_pk_fma_f32 v[16:17], v[16:17], v[68:69], v[44:45] op_sel:[0,1,0] op_sel_hi:[1,1,1]
	v_pk_mul_f32 v[44:45], v[72:73], v[62:63] op_sel_hi:[1,0]
	v_pk_fma_f32 v[38:39], v[14:15], v[56:57], v[38:39] op_sel:[0,1,0] op_sel_hi:[1,1,1]
	v_pk_fma_f32 v[18:19], v[18:19], v[70:71], v[42:43] op_sel:[0,0,0] op_sel_hi:[1,0,1]
	v_pk_fma_f32 v[38:39], v[16:17], v[58:59], v[38:39] op_sel:[0,1,0] op_sel_hi:[1,1,1]
	v_pk_fma_f32 v[20:21], v[20:21], v[70:71], v[44:45] op_sel:[0,1,0] op_sel_hi:[1,1,1]
	v_pk_fma_f32 v[38:39], v[18:19], v[60:61], v[38:39] op_sel:[0,1,0] op_sel_hi:[1,1,1]
	v_pk_fma_f32 v[38:39], v[20:21], v[62:63], v[38:39] op_sel:[0,1,0] op_sel_hi:[1,1,1]
	s_add_u32 s14, s14, 0x1000
	s_addc_u32 s15, s15, 0
	v_add_f32_dpp v38, v38, v38 row_ror:8 row_mask:0xf bank_mask:0x3 bound_ctrl:1
	v_add_f32_dpp v38, v39, v39 row_ror:8 row_mask:0xf bank_mask:0xc bound_ctrl:1
	ds_read_b64 v[104:105], v3 offset:20992
	ds_read_b128 v[80:83], v2 offset:1280
	v_add_f32_dpp v38, v38, v38 row_half_mirror row_mask:0xf bank_mask:0xf bound_ctrl:1
	ds_read_b128 v[96:99], v2 offset:17152
	ds_read_b128 v[84:87], v2 offset:1536
	v_add_f32_dpp v38, v38, v38 quad_perm:[1,0,3,2] row_mask:0xf bank_mask:0xf bound_ctrl:1
	ds_read_b128 v[88:91], v2 offset:1792
	ds_read_b128 v[100:103], v2 offset:17408
	v_add_f32_dpp v38, v38, v38 quad_perm:[2,3,0,1] row_mask:0xf bank_mask:0xf bound_ctrl:1
	ds_read_b128 v[92:95], v2 offset:2048
	v_cvt_pk_bf16_f32 v47, v38, v38
	s_mov_b64 exec, s[2:3]
	global_store_short v28, v47, s[14:15] offset:-4096
	s_mov_b64 exec, -1
	s_waitcnt lgkmcnt(4)
	v_pk_mul_f32 v[42:43], v[104:105], v[80:81] op_sel_hi:[1,0]
	v_pk_mul_f32 v[44:45], v[104:105], v[82:83] op_sel_hi:[1,0]
	v_pk_fma_f32 v[6:7], v[6:7], v[96:97], v[42:43] op_sel:[0,0,0] op_sel_hi:[1,0,1]
	s_waitcnt lgkmcnt(3)
	v_pk_mul_f32 v[42:43], v[104:105], v[84:85] op_sel_hi:[1,0]
	v_pk_fma_f32 v[8:9], v[8:9], v[96:97], v[44:45] op_sel:[0,1,0] op_sel_hi:[1,1,1]
	v_pk_mul_f32 v[44:45], v[104:105], v[86:87] op_sel_hi:[1,0]
	v_pk_mul_f32 v[38:39], v[6:7], v[80:81] op_sel:[0,1] op_sel_hi:[1,1]
	v_pk_fma_f32 v[10:11], v[10:11], v[98:99], v[42:43] op_sel:[0,0,0] op_sel_hi:[1,0,1]
	s_waitcnt lgkmcnt(1)
	v_pk_mul_f32 v[42:43], v[104:105], v[88:89] op_sel_hi:[1,0]
	v_pk_fma_f32 v[38:39], v[8:9], v[82:83], v[38:39] op_sel:[0,1,0] op_sel_hi:[1,1,1]
	v_pk_fma_f32 v[12:13], v[12:13], v[98:99], v[44:45] op_sel:[0,1,0] op_sel_hi:[1,1,1]
	v_pk_mul_f32 v[44:45], v[104:105], v[90:91] op_sel_hi:[1,0]
	v_pk_fma_f32 v[38:39], v[10:11], v[84:85], v[38:39] op_sel:[0,1,0] op_sel_hi:[1,1,1]
	v_pk_fma_f32 v[14:15], v[14:15], v[100:101], v[42:43] op_sel:[0,0,0] op_sel_hi:[1,0,1]
	s_waitcnt lgkmcnt(0)
	v_pk_mul_f32 v[42:43], v[104:105], v[92:93] op_sel_hi:[1,0]
	v_pk_fma_f32 v[38:39], v[12:13], v[86:87], v[38:39] op_sel:[0,1,0] op_sel_hi:[1,1,1]
	v_pk_fma_f32 v[16:17], v[16:17], v[100:101], v[44:45] op_sel:[0,1,0] op_sel_hi:[1,1,1]
	v_pk_mul_f32 v[44:45], v[104:105], v[94:95] op_sel_hi:[1,0]
	v_pk_fma_f32 v[38:39], v[14:15], v[88:89], v[38:39] op_sel:[0,1,0] op_sel_hi:[1,1,1]
	v_pk_fma_f32 v[18:19], v[18:19], v[102:103], v[42:43] op_sel:[0,0,0] op_sel_hi:[1,0,1]
	v_pk_fma_f32 v[38:39], v[16:17], v[90:91], v[38:39] op_sel:[0,1,0] op_sel_hi:[1,1,1]
	v_pk_fma_f32 v[20:21], v[20:21], v[102:103], v[44:45] op_sel:[0,1,0] op_sel_hi:[1,1,1]
	v_pk_fma_f32 v[38:39], v[18:19], v[92:93], v[38:39] op_sel:[0,1,0] op_sel_hi:[1,1,1]
	v_pk_fma_f32 v[38:39], v[20:21], v[94:95], v[38:39] op_sel:[0,1,0] op_sel_hi:[1,1,1]
	s_add_u32 s14, s14, 0x1000
	s_addc_u32 s15, s15, 0
	v_add_f32_dpp v38, v38, v38 row_ror:8 row_mask:0xf bank_mask:0x3 bound_ctrl:1
	v_add_f32_dpp v38, v39, v39 row_ror:8 row_mask:0xf bank_mask:0xc bound_ctrl:1
	ds_read_b64 v[72:73], v3 offset:21248
	ds_read_b128 v[48:51], v2 offset:2304
	v_add_f32_dpp v38, v38, v38 row_half_mirror row_mask:0xf bank_mask:0xf bound_ctrl:1
	ds_read_b128 v[64:67], v2 offset:17664
	ds_read_b128 v[52:55], v2 offset:2560
	v_add_f32_dpp v38, v38, v38 quad_perm:[1,0,3,2] row_mask:0xf bank_mask:0xf bound_ctrl:1
	ds_read_b128 v[56:59], v2 offset:2816
	ds_read_b128 v[68:71], v2 offset:17920
	v_add_f32_dpp v38, v38, v38 quad_perm:[2,3,0,1] row_mask:0xf bank_mask:0xf bound_ctrl:1
	ds_read_b128 v[60:63], v2 offset:3072
	v_cvt_pk_bf16_f32 v47, v38, v38
	s_mov_b64 exec, s[2:3]
	global_store_short v28, v47, s[14:15] offset:-4096
	s_mov_b64 exec, -1
	s_waitcnt lgkmcnt(4)
	v_pk_mul_f32 v[42:43], v[72:73], v[48:49] op_sel_hi:[1,0]
	v_pk_mul_f32 v[44:45], v[72:73], v[50:51] op_sel_hi:[1,0]
	v_pk_fma_f32 v[6:7], v[6:7], v[64:65], v[42:43] op_sel:[0,0,0] op_sel_hi:[1,0,1]
	s_waitcnt lgkmcnt(3)
	v_pk_mul_f32 v[42:43], v[72:73], v[52:53] op_sel_hi:[1,0]
	v_pk_fma_f32 v[8:9], v[8:9], v[64:65], v[44:45] op_sel:[0,1,0] op_sel_hi:[1,1,1]
	v_pk_mul_f32 v[44:45], v[72:73], v[54:55] op_sel_hi:[1,0]
	v_pk_mul_f32 v[38:39], v[6:7], v[48:49] op_sel:[0,1] op_sel_hi:[1,1]
	v_pk_fma_f32 v[10:11], v[10:11], v[66:67], v[42:43] op_sel:[0,0,0] op_sel_hi:[1,0,1]
	s_waitcnt lgkmcnt(1)
	v_pk_mul_f32 v[42:43], v[72:73], v[56:57] op_sel_hi:[1,0]
	v_pk_fma_f32 v[38:39], v[8:9], v[50:51], v[38:39] op_sel:[0,1,0] op_sel_hi:[1,1,1]
	v_pk_fma_f32 v[12:13], v[12:13], v[66:67], v[44:45] op_sel:[0,1,0] op_sel_hi:[1,1,1]
	v_pk_mul_f32 v[44:45], v[72:73], v[58:59] op_sel_hi:[1,0]
	v_pk_fma_f32 v[38:39], v[10:11], v[52:53], v[38:39] op_sel:[0,1,0] op_sel_hi:[1,1,1]
	v_pk_fma_f32 v[14:15], v[14:15], v[68:69], v[42:43] op_sel:[0,0,0] op_sel_hi:[1,0,1]
	s_waitcnt lgkmcnt(0)
	v_pk_mul_f32 v[42:43], v[72:73], v[60:61] op_sel_hi:[1,0]
	v_pk_fma_f32 v[38:39], v[12:13], v[54:55], v[38:39] op_sel:[0,1,0] op_sel_hi:[1,1,1]
	v_pk_fma_f32 v[16:17], v[16:17], v[68:69], v[44:45] op_sel:[0,1,0] op_sel_hi:[1,1,1]
	v_pk_mul_f32 v[44:45], v[72:73], v[62:63] op_sel_hi:[1,0]
	v_pk_fma_f32 v[38:39], v[14:15], v[56:57], v[38:39] op_sel:[0,1,0] op_sel_hi:[1,1,1]
	v_pk_fma_f32 v[18:19], v[18:19], v[70:71], v[42:43] op_sel:[0,0,0] op_sel_hi:[1,0,1]
	v_pk_fma_f32 v[38:39], v[16:17], v[58:59], v[38:39] op_sel:[0,1,0] op_sel_hi:[1,1,1]
	v_pk_fma_f32 v[20:21], v[20:21], v[70:71], v[44:45] op_sel:[0,1,0] op_sel_hi:[1,1,1]
	v_pk_fma_f32 v[38:39], v[18:19], v[60:61], v[38:39] op_sel:[0,1,0] op_sel_hi:[1,1,1]
	v_pk_fma_f32 v[38:39], v[20:21], v[62:63], v[38:39] op_sel:[0,1,0] op_sel_hi:[1,1,1]
	s_add_u32 s14, s14, 0x1000
	s_addc_u32 s15, s15, 0
	v_add_f32_dpp v38, v38, v38 row_ror:8 row_mask:0xf bank_mask:0x3 bound_ctrl:1
	v_add_f32_dpp v38, v39, v39 row_ror:8 row_mask:0xf bank_mask:0xc bound_ctrl:1
	ds_read_b64 v[104:105], v3 offset:21504
	ds_read_b128 v[80:83], v2 offset:3328
	v_add_f32_dpp v38, v38, v38 row_half_mirror row_mask:0xf bank_mask:0xf bound_ctrl:1
	ds_read_b128 v[96:99], v2 offset:18176
	ds_read_b128 v[84:87], v2 offset:3584
	v_add_f32_dpp v38, v38, v38 quad_perm:[1,0,3,2] row_mask:0xf bank_mask:0xf bound_ctrl:1
	ds_read_b128 v[88:91], v2 offset:3840
	ds_read_b128 v[100:103], v2 offset:18432
	v_add_f32_dpp v38, v38, v38 quad_perm:[2,3,0,1] row_mask:0xf bank_mask:0xf bound_ctrl:1
	ds_read_b128 v[92:95], v2 offset:4096
	v_cvt_pk_bf16_f32 v47, v38, v38
	s_mov_b64 exec, s[2:3]
	global_store_short v28, v47, s[14:15] offset:-4096
	s_mov_b64 exec, -1
	s_waitcnt lgkmcnt(4)
	v_pk_mul_f32 v[42:43], v[104:105], v[80:81] op_sel_hi:[1,0]
	v_pk_mul_f32 v[44:45], v[104:105], v[82:83] op_sel_hi:[1,0]
	v_pk_fma_f32 v[6:7], v[6:7], v[96:97], v[42:43] op_sel:[0,0,0] op_sel_hi:[1,0,1]
	s_waitcnt lgkmcnt(3)
	v_pk_mul_f32 v[42:43], v[104:105], v[84:85] op_sel_hi:[1,0]
	v_pk_fma_f32 v[8:9], v[8:9], v[96:97], v[44:45] op_sel:[0,1,0] op_sel_hi:[1,1,1]
	v_pk_mul_f32 v[44:45], v[104:105], v[86:87] op_sel_hi:[1,0]
	v_pk_mul_f32 v[38:39], v[6:7], v[80:81] op_sel:[0,1] op_sel_hi:[1,1]
	v_pk_fma_f32 v[10:11], v[10:11], v[98:99], v[42:43] op_sel:[0,0,0] op_sel_hi:[1,0,1]
	s_waitcnt lgkmcnt(1)
	v_pk_mul_f32 v[42:43], v[104:105], v[88:89] op_sel_hi:[1,0]
	v_pk_fma_f32 v[38:39], v[8:9], v[82:83], v[38:39] op_sel:[0,1,0] op_sel_hi:[1,1,1]
	v_pk_fma_f32 v[12:13], v[12:13], v[98:99], v[44:45] op_sel:[0,1,0] op_sel_hi:[1,1,1]
	v_pk_mul_f32 v[44:45], v[104:105], v[90:91] op_sel_hi:[1,0]
	v_pk_fma_f32 v[38:39], v[10:11], v[84:85], v[38:39] op_sel:[0,1,0] op_sel_hi:[1,1,1]
	v_pk_fma_f32 v[14:15], v[14:15], v[100:101], v[42:43] op_sel:[0,0,0] op_sel_hi:[1,0,1]
	s_waitcnt lgkmcnt(0)
	v_pk_mul_f32 v[42:43], v[104:105], v[92:93] op_sel_hi:[1,0]
	v_pk_fma_f32 v[38:39], v[12:13], v[86:87], v[38:39] op_sel:[0,1,0] op_sel_hi:[1,1,1]
	v_pk_fma_f32 v[16:17], v[16:17], v[100:101], v[44:45] op_sel:[0,1,0] op_sel_hi:[1,1,1]
	v_pk_mul_f32 v[44:45], v[104:105], v[94:95] op_sel_hi:[1,0]
	v_pk_fma_f32 v[38:39], v[14:15], v[88:89], v[38:39] op_sel:[0,1,0] op_sel_hi:[1,1,1]
	v_pk_fma_f32 v[18:19], v[18:19], v[102:103], v[42:43] op_sel:[0,0,0] op_sel_hi:[1,0,1]
	v_pk_fma_f32 v[38:39], v[16:17], v[90:91], v[38:39] op_sel:[0,1,0] op_sel_hi:[1,1,1]
	v_pk_fma_f32 v[20:21], v[20:21], v[102:103], v[44:45] op_sel:[0,1,0] op_sel_hi:[1,1,1]
	v_pk_fma_f32 v[38:39], v[18:19], v[92:93], v[38:39] op_sel:[0,1,0] op_sel_hi:[1,1,1]
	v_pk_fma_f32 v[38:39], v[20:21], v[94:95], v[38:39] op_sel:[0,1,0] op_sel_hi:[1,1,1]
	s_add_u32 s14, s14, 0x1000
	s_addc_u32 s15, s15, 0
	v_add_f32_dpp v38, v38, v38 row_ror:8 row_mask:0xf bank_mask:0x3 bound_ctrl:1
	v_add_f32_dpp v38, v39, v39 row_ror:8 row_mask:0xf bank_mask:0xc bound_ctrl:1
	ds_read_b64 v[72:73], v3 offset:21760
	ds_read_b128 v[48:51], v2 offset:4352
	v_add_f32_dpp v38, v38, v38 row_half_mirror row_mask:0xf bank_mask:0xf bound_ctrl:1
	ds_read_b128 v[64:67], v2 offset:18688
	ds_read_b128 v[52:55], v2 offset:4608
	v_add_f32_dpp v38, v38, v38 quad_perm:[1,0,3,2] row_mask:0xf bank_mask:0xf bound_ctrl:1
	ds_read_b128 v[56:59], v2 offset:4864
	ds_read_b128 v[68:71], v2 offset:18944
	v_add_f32_dpp v38, v38, v38 quad_perm:[2,3,0,1] row_mask:0xf bank_mask:0xf bound_ctrl:1
	ds_read_b128 v[60:63], v2 offset:5120
	v_cvt_pk_bf16_f32 v47, v38, v38
	s_mov_b64 exec, s[2:3]
	global_store_short v28, v47, s[14:15] offset:-4096
	s_mov_b64 exec, -1
	s_waitcnt lgkmcnt(4)
	v_pk_mul_f32 v[42:43], v[72:73], v[48:49] op_sel_hi:[1,0]
	v_pk_mul_f32 v[44:45], v[72:73], v[50:51] op_sel_hi:[1,0]
	v_pk_fma_f32 v[6:7], v[6:7], v[64:65], v[42:43] op_sel:[0,0,0] op_sel_hi:[1,0,1]
	s_waitcnt lgkmcnt(3)
	v_pk_mul_f32 v[42:43], v[72:73], v[52:53] op_sel_hi:[1,0]
	v_pk_fma_f32 v[8:9], v[8:9], v[64:65], v[44:45] op_sel:[0,1,0] op_sel_hi:[1,1,1]
	v_pk_mul_f32 v[44:45], v[72:73], v[54:55] op_sel_hi:[1,0]
	v_pk_mul_f32 v[38:39], v[6:7], v[48:49] op_sel:[0,1] op_sel_hi:[1,1]
	v_pk_fma_f32 v[10:11], v[10:11], v[66:67], v[42:43] op_sel:[0,0,0] op_sel_hi:[1,0,1]
	s_waitcnt lgkmcnt(1)
	v_pk_mul_f32 v[42:43], v[72:73], v[56:57] op_sel_hi:[1,0]
	v_pk_fma_f32 v[38:39], v[8:9], v[50:51], v[38:39] op_sel:[0,1,0] op_sel_hi:[1,1,1]
	v_pk_fma_f32 v[12:13], v[12:13], v[66:67], v[44:45] op_sel:[0,1,0] op_sel_hi:[1,1,1]
	v_pk_mul_f32 v[44:45], v[72:73], v[58:59] op_sel_hi:[1,0]
	v_pk_fma_f32 v[38:39], v[10:11], v[52:53], v[38:39] op_sel:[0,1,0] op_sel_hi:[1,1,1]
	v_pk_fma_f32 v[14:15], v[14:15], v[68:69], v[42:43] op_sel:[0,0,0] op_sel_hi:[1,0,1]
	s_waitcnt lgkmcnt(0)
	v_pk_mul_f32 v[42:43], v[72:73], v[60:61] op_sel_hi:[1,0]
	v_pk_fma_f32 v[38:39], v[12:13], v[54:55], v[38:39] op_sel:[0,1,0] op_sel_hi:[1,1,1]
	v_pk_fma_f32 v[16:17], v[16:17], v[68:69], v[44:45] op_sel:[0,1,0] op_sel_hi:[1,1,1]
	v_pk_mul_f32 v[44:45], v[72:73], v[62:63] op_sel_hi:[1,0]
	v_pk_fma_f32 v[38:39], v[14:15], v[56:57], v[38:39] op_sel:[0,1,0] op_sel_hi:[1,1,1]
	v_pk_fma_f32 v[18:19], v[18:19], v[70:71], v[42:43] op_sel:[0,0,0] op_sel_hi:[1,0,1]
	v_pk_fma_f32 v[38:39], v[16:17], v[58:59], v[38:39] op_sel:[0,1,0] op_sel_hi:[1,1,1]
	v_pk_fma_f32 v[20:21], v[20:21], v[70:71], v[44:45] op_sel:[0,1,0] op_sel_hi:[1,1,1]
	v_pk_fma_f32 v[38:39], v[18:19], v[60:61], v[38:39] op_sel:[0,1,0] op_sel_hi:[1,1,1]
	v_pk_fma_f32 v[38:39], v[20:21], v[62:63], v[38:39] op_sel:[0,1,0] op_sel_hi:[1,1,1]
	s_add_u32 s14, s14, 0x1000
	s_addc_u32 s15, s15, 0
	v_add_f32_dpp v38, v38, v38 row_ror:8 row_mask:0xf bank_mask:0x3 bound_ctrl:1
	v_add_f32_dpp v38, v39, v39 row_ror:8 row_mask:0xf bank_mask:0xc bound_ctrl:1
	ds_read_b64 v[104:105], v3 offset:22016
	ds_read_b128 v[80:83], v2 offset:5376
	v_add_f32_dpp v38, v38, v38 row_half_mirror row_mask:0xf bank_mask:0xf bound_ctrl:1
	ds_read_b128 v[96:99], v2 offset:19200
	ds_read_b128 v[84:87], v2 offset:5632
	v_add_f32_dpp v38, v38, v38 quad_perm:[1,0,3,2] row_mask:0xf bank_mask:0xf bound_ctrl:1
	ds_read_b128 v[88:91], v2 offset:5888
	ds_read_b128 v[100:103], v2 offset:19456
	v_add_f32_dpp v38, v38, v38 quad_perm:[2,3,0,1] row_mask:0xf bank_mask:0xf bound_ctrl:1
	ds_read_b128 v[92:95], v2 offset:6144
	v_cvt_pk_bf16_f32 v47, v38, v38
	s_mov_b64 exec, s[2:3]
	global_store_short v28, v47, s[14:15] offset:-4096
	s_mov_b64 exec, -1
	s_waitcnt lgkmcnt(4)
	v_pk_mul_f32 v[42:43], v[104:105], v[80:81] op_sel_hi:[1,0]
	v_pk_mul_f32 v[44:45], v[104:105], v[82:83] op_sel_hi:[1,0]
	v_pk_fma_f32 v[6:7], v[6:7], v[96:97], v[42:43] op_sel:[0,0,0] op_sel_hi:[1,0,1]
	s_waitcnt lgkmcnt(3)
	v_pk_mul_f32 v[42:43], v[104:105], v[84:85] op_sel_hi:[1,0]
	v_pk_fma_f32 v[8:9], v[8:9], v[96:97], v[44:45] op_sel:[0,1,0] op_sel_hi:[1,1,1]
	v_pk_mul_f32 v[44:45], v[104:105], v[86:87] op_sel_hi:[1,0]
	v_pk_mul_f32 v[38:39], v[6:7], v[80:81] op_sel:[0,1] op_sel_hi:[1,1]
	v_pk_fma_f32 v[10:11], v[10:11], v[98:99], v[42:43] op_sel:[0,0,0] op_sel_hi:[1,0,1]
	s_waitcnt lgkmcnt(1)
	v_pk_mul_f32 v[42:43], v[104:105], v[88:89] op_sel_hi:[1,0]
	v_pk_fma_f32 v[38:39], v[8:9], v[82:83], v[38:39] op_sel:[0,1,0] op_sel_hi:[1,1,1]
	v_pk_fma_f32 v[12:13], v[12:13], v[98:99], v[44:45] op_sel:[0,1,0] op_sel_hi:[1,1,1]
	v_pk_mul_f32 v[44:45], v[104:105], v[90:91] op_sel_hi:[1,0]
	v_pk_fma_f32 v[38:39], v[10:11], v[84:85], v[38:39] op_sel:[0,1,0] op_sel_hi:[1,1,1]
	v_pk_fma_f32 v[14:15], v[14:15], v[100:101], v[42:43] op_sel:[0,0,0] op_sel_hi:[1,0,1]
	s_waitcnt lgkmcnt(0)
	v_pk_mul_f32 v[42:43], v[104:105], v[92:93] op_sel_hi:[1,0]
	v_pk_fma_f32 v[38:39], v[12:13], v[86:87], v[38:39] op_sel:[0,1,0] op_sel_hi:[1,1,1]
	v_pk_fma_f32 v[16:17], v[16:17], v[100:101], v[44:45] op_sel:[0,1,0] op_sel_hi:[1,1,1]
	v_pk_mul_f32 v[44:45], v[104:105], v[94:95] op_sel_hi:[1,0]
	v_pk_fma_f32 v[38:39], v[14:15], v[88:89], v[38:39] op_sel:[0,1,0] op_sel_hi:[1,1,1]
	v_pk_fma_f32 v[18:19], v[18:19], v[102:103], v[42:43] op_sel:[0,0,0] op_sel_hi:[1,0,1]
	v_pk_fma_f32 v[38:39], v[16:17], v[90:91], v[38:39] op_sel:[0,1,0] op_sel_hi:[1,1,1]
	v_pk_fma_f32 v[20:21], v[20:21], v[102:103], v[44:45] op_sel:[0,1,0] op_sel_hi:[1,1,1]
	v_pk_fma_f32 v[38:39], v[18:19], v[92:93], v[38:39] op_sel:[0,1,0] op_sel_hi:[1,1,1]
	v_pk_fma_f32 v[38:39], v[20:21], v[94:95], v[38:39] op_sel:[0,1,0] op_sel_hi:[1,1,1]
	s_add_u32 s14, s14, 0x1000
	s_addc_u32 s15, s15, 0
	v_add_f32_dpp v38, v38, v38 row_ror:8 row_mask:0xf bank_mask:0x3 bound_ctrl:1
	v_add_f32_dpp v38, v39, v39 row_ror:8 row_mask:0xf bank_mask:0xc bound_ctrl:1
	ds_read_b64 v[72:73], v3 offset:22272
	ds_read_b128 v[48:51], v2 offset:6400
	v_add_f32_dpp v38, v38, v38 row_half_mirror row_mask:0xf bank_mask:0xf bound_ctrl:1
	ds_read_b128 v[64:67], v2 offset:19712
	ds_read_b128 v[52:55], v2 offset:6656
	v_add_f32_dpp v38, v38, v38 quad_perm:[1,0,3,2] row_mask:0xf bank_mask:0xf bound_ctrl:1
	ds_read_b128 v[56:59], v2 offset:6912
	ds_read_b128 v[68:71], v2 offset:19968
	v_add_f32_dpp v38, v38, v38 quad_perm:[2,3,0,1] row_mask:0xf bank_mask:0xf bound_ctrl:1
	ds_read_b128 v[60:63], v2 offset:7168
	v_cvt_pk_bf16_f32 v47, v38, v38
	s_mov_b64 exec, s[2:3]
	global_store_short v28, v47, s[14:15] offset:-4096
	s_mov_b64 exec, -1
	s_waitcnt lgkmcnt(4)
	v_pk_mul_f32 v[42:43], v[72:73], v[48:49] op_sel_hi:[1,0]
	v_pk_mul_f32 v[44:45], v[72:73], v[50:51] op_sel_hi:[1,0]
	v_pk_fma_f32 v[6:7], v[6:7], v[64:65], v[42:43] op_sel:[0,0,0] op_sel_hi:[1,0,1]
	s_waitcnt lgkmcnt(3)
	v_pk_mul_f32 v[42:43], v[72:73], v[52:53] op_sel_hi:[1,0]
	v_pk_fma_f32 v[8:9], v[8:9], v[64:65], v[44:45] op_sel:[0,1,0] op_sel_hi:[1,1,1]
	v_pk_mul_f32 v[44:45], v[72:73], v[54:55] op_sel_hi:[1,0]
	v_pk_mul_f32 v[38:39], v[6:7], v[48:49] op_sel:[0,1] op_sel_hi:[1,1]
	v_pk_fma_f32 v[10:11], v[10:11], v[66:67], v[42:43] op_sel:[0,0,0] op_sel_hi:[1,0,1]
	s_waitcnt lgkmcnt(1)
	v_pk_mul_f32 v[42:43], v[72:73], v[56:57] op_sel_hi:[1,0]
	v_pk_fma_f32 v[38:39], v[8:9], v[50:51], v[38:39] op_sel:[0,1,0] op_sel_hi:[1,1,1]
	v_pk_fma_f32 v[12:13], v[12:13], v[66:67], v[44:45] op_sel:[0,1,0] op_sel_hi:[1,1,1]
	v_pk_mul_f32 v[44:45], v[72:73], v[58:59] op_sel_hi:[1,0]
	v_pk_fma_f32 v[38:39], v[10:11], v[52:53], v[38:39] op_sel:[0,1,0] op_sel_hi:[1,1,1]
	v_pk_fma_f32 v[14:15], v[14:15], v[68:69], v[42:43] op_sel:[0,0,0] op_sel_hi:[1,0,1]
	s_waitcnt lgkmcnt(0)
	v_pk_mul_f32 v[42:43], v[72:73], v[60:61] op_sel_hi:[1,0]
	v_pk_fma_f32 v[38:39], v[12:13], v[54:55], v[38:39] op_sel:[0,1,0] op_sel_hi:[1,1,1]
	v_pk_fma_f32 v[16:17], v[16:17], v[68:69], v[44:45] op_sel:[0,1,0] op_sel_hi:[1,1,1]
	v_pk_mul_f32 v[44:45], v[72:73], v[62:63] op_sel_hi:[1,0]
	v_pk_fma_f32 v[38:39], v[14:15], v[56:57], v[38:39] op_sel:[0,1,0] op_sel_hi:[1,1,1]
	v_pk_fma_f32 v[18:19], v[18:19], v[70:71], v[42:43] op_sel:[0,0,0] op_sel_hi:[1,0,1]
	v_pk_fma_f32 v[38:39], v[16:17], v[58:59], v[38:39] op_sel:[0,1,0] op_sel_hi:[1,1,1]
	v_pk_fma_f32 v[20:21], v[20:21], v[70:71], v[44:45] op_sel:[0,1,0] op_sel_hi:[1,1,1]
	v_pk_fma_f32 v[38:39], v[18:19], v[60:61], v[38:39] op_sel:[0,1,0] op_sel_hi:[1,1,1]
	v_pk_fma_f32 v[38:39], v[20:21], v[62:63], v[38:39] op_sel:[0,1,0] op_sel_hi:[1,1,1]
	s_add_u32 s14, s14, 0x1000
	s_addc_u32 s15, s15, 0
	v_add_f32_dpp v38, v38, v38 row_ror:8 row_mask:0xf bank_mask:0x3 bound_ctrl:1
	v_add_f32_dpp v38, v39, v39 row_ror:8 row_mask:0xf bank_mask:0xc bound_ctrl:1
	ds_read_b64 v[104:105], v3 offset:22528
	ds_read_b128 v[80:83], v2 offset:7424
	v_add_f32_dpp v38, v38, v38 row_half_mirror row_mask:0xf bank_mask:0xf bound_ctrl:1
	ds_read_b128 v[96:99], v2 offset:20224
	ds_read_b128 v[84:87], v2 offset:7680
	v_add_f32_dpp v38, v38, v38 quad_perm:[1,0,3,2] row_mask:0xf bank_mask:0xf bound_ctrl:1
	ds_read_b128 v[88:91], v2 offset:7936
	ds_read_b128 v[100:103], v2 offset:20480
	v_add_f32_dpp v38, v38, v38 quad_perm:[2,3,0,1] row_mask:0xf bank_mask:0xf bound_ctrl:1
	ds_read_b128 v[92:95], v2 offset:8192
	v_cvt_pk_bf16_f32 v47, v38, v38
	s_mov_b64 exec, s[2:3]
	global_store_short v28, v47, s[14:15] offset:-4096
	s_mov_b64 exec, -1
	s_waitcnt lgkmcnt(4)
	v_pk_mul_f32 v[42:43], v[104:105], v[80:81] op_sel_hi:[1,0]
	v_pk_mul_f32 v[44:45], v[104:105], v[82:83] op_sel_hi:[1,0]
	v_pk_fma_f32 v[6:7], v[6:7], v[96:97], v[42:43] op_sel:[0,0,0] op_sel_hi:[1,0,1]
	s_waitcnt lgkmcnt(3)
	v_pk_mul_f32 v[42:43], v[104:105], v[84:85] op_sel_hi:[1,0]
	v_pk_fma_f32 v[8:9], v[8:9], v[96:97], v[44:45] op_sel:[0,1,0] op_sel_hi:[1,1,1]
	v_pk_mul_f32 v[44:45], v[104:105], v[86:87] op_sel_hi:[1,0]
	v_pk_mul_f32 v[38:39], v[6:7], v[80:81] op_sel:[0,1] op_sel_hi:[1,1]
	v_pk_fma_f32 v[10:11], v[10:11], v[98:99], v[42:43] op_sel:[0,0,0] op_sel_hi:[1,0,1]
	s_waitcnt lgkmcnt(1)
	v_pk_mul_f32 v[42:43], v[104:105], v[88:89] op_sel_hi:[1,0]
	v_pk_fma_f32 v[38:39], v[8:9], v[82:83], v[38:39] op_sel:[0,1,0] op_sel_hi:[1,1,1]
	v_pk_fma_f32 v[12:13], v[12:13], v[98:99], v[44:45] op_sel:[0,1,0] op_sel_hi:[1,1,1]
	v_pk_mul_f32 v[44:45], v[104:105], v[90:91] op_sel_hi:[1,0]
	v_pk_fma_f32 v[38:39], v[10:11], v[84:85], v[38:39] op_sel:[0,1,0] op_sel_hi:[1,1,1]
	v_pk_fma_f32 v[14:15], v[14:15], v[100:101], v[42:43] op_sel:[0,0,0] op_sel_hi:[1,0,1]
	s_waitcnt lgkmcnt(0)
	v_pk_mul_f32 v[42:43], v[104:105], v[92:93] op_sel_hi:[1,0]
	v_pk_fma_f32 v[38:39], v[12:13], v[86:87], v[38:39] op_sel:[0,1,0] op_sel_hi:[1,1,1]
	v_pk_fma_f32 v[16:17], v[16:17], v[100:101], v[44:45] op_sel:[0,1,0] op_sel_hi:[1,1,1]
	v_pk_mul_f32 v[44:45], v[104:105], v[94:95] op_sel_hi:[1,0]
	v_pk_fma_f32 v[38:39], v[14:15], v[88:89], v[38:39] op_sel:[0,1,0] op_sel_hi:[1,1,1]
	v_pk_fma_f32 v[18:19], v[18:19], v[102:103], v[42:43] op_sel:[0,0,0] op_sel_hi:[1,0,1]
	v_pk_fma_f32 v[38:39], v[16:17], v[90:91], v[38:39] op_sel:[0,1,0] op_sel_hi:[1,1,1]
	v_pk_fma_f32 v[20:21], v[20:21], v[102:103], v[44:45] op_sel:[0,1,0] op_sel_hi:[1,1,1]
	v_pk_fma_f32 v[38:39], v[18:19], v[92:93], v[38:39] op_sel:[0,1,0] op_sel_hi:[1,1,1]
	v_pk_fma_f32 v[38:39], v[20:21], v[94:95], v[38:39] op_sel:[0,1,0] op_sel_hi:[1,1,1]
	s_add_u32 s14, s14, 0x1000
	s_addc_u32 s15, s15, 0
	v_add_f32_dpp v38, v38, v38 row_ror:8 row_mask:0xf bank_mask:0x3 bound_ctrl:1
	v_add_f32_dpp v38, v39, v39 row_ror:8 row_mask:0xf bank_mask:0xc bound_ctrl:1
	ds_read_b64 v[72:73], v3 offset:45312
	ds_read_b128 v[48:51], v2 offset:24832
	v_add_f32_dpp v38, v38, v38 row_half_mirror row_mask:0xf bank_mask:0xf bound_ctrl:1
	ds_read_b128 v[64:67], v2 offset:41216
	ds_read_b128 v[52:55], v2 offset:25088
	v_add_f32_dpp v38, v38, v38 quad_perm:[1,0,3,2] row_mask:0xf bank_mask:0xf bound_ctrl:1
	ds_read_b128 v[56:59], v2 offset:25344
	ds_read_b128 v[68:71], v2 offset:41472
	v_add_f32_dpp v38, v38, v38 quad_perm:[2,3,0,1] row_mask:0xf bank_mask:0xf bound_ctrl:1
	ds_read_b128 v[60:63], v2 offset:25600
	v_cvt_pk_bf16_f32 v47, v38, v38
	s_mov_b64 exec, s[2:3]
	global_store_short v28, v47, s[14:15] offset:-4096
	s_mov_b64 exec, -1
	s_waitcnt vmcnt(8)
	v_lshlrev_b32_e32 v144, 16, v110
	v_lshlrev_b32_e32 v145, 16, v111
	v_and_b32_e32 v146, s17, v110
	v_and_b32_e32 v147, s17, v111
	v_lshlrev_b32_e32 v148, 16, v112
	v_lshlrev_b32_e32 v149, 16, v113
	v_and_b32_e32 v150, s17, v112
	v_and_b32_e32 v151, s17, v113
	v_lshlrev_b32_e32 v152, 16, v114
	v_and_b32_e32 v153, s17, v114
	v_rcp_f32_e32 v25, v24
	v_mul_f32_e32 v149, v24, v149
	v_mul_f32_e32 v151, v24, v151
	v_mul_f32_e32 v145, 0x3db504f3, v145
	v_mul_f32_e32 v147, 0x3db504f3, v147
	v_cndmask_b32_e64 v27, 1.0, v25, s[20:21]
	v_mul_f32_e32 v24, v24, v26
	v_mul_f32_e32 v152, v27, v152
	v_mul_f32_e32 v153, v27, v153
	ds_write_b128 v29, v[144:147] offset:49408
	ds_write_b128 v29, v[148:151] offset:57600
	ds_write_b64 v30, v[116:117] offset:49408
	ds_write_b64 v31, v[152:153] offset:49408
	s_add_i32 s16, s16, 8
	s_waitcnt lgkmcnt(0)
	s_barrier
	s_cmpk_lt_u32 s16, 0x800
	s_cbranch_scc0 .Lgla2_done
	global_load_dword v110, v32, s[10:11]
	global_load_dword v111, v32, s[10:11] offset:-1024
	global_load_dword v112, v33, s[10:11]
	global_load_dword v113, v33, s[10:11] offset:-1024
	global_load_dword v114, v34, s[10:11]
	global_load_dword v116, v35, s[12:13]
	global_load_dword v117, v35, s[12:13] offset:4
	s_add_u32 s10, s10, 0x18000
	s_addc_u32 s11, s11, 0
	s_add_u32 s12, s12, 0x4000
	s_addc_u32 s13, s13, 0
	s_waitcnt lgkmcnt(4)
	v_pk_mul_f32 v[42:43], v[72:73], v[48:49] op_sel_hi:[1,0]
	v_pk_mul_f32 v[44:45], v[72:73], v[50:51] op_sel_hi:[1,0]
	v_pk_fma_f32 v[6:7], v[6:7], v[64:65], v[42:43] op_sel:[0,0,0] op_sel_hi:[1,0,1]
	s_waitcnt lgkmcnt(3)
	v_pk_mul_f32 v[42:43], v[72:73], v[52:53] op_sel_hi:[1,0]
	v_pk_fma_f32 v[8:9], v[8:9], v[64:65], v[44:45] op_sel:[0,1,0] op_sel_hi:[1,1,1]
	v_pk_mul_f32 v[44:45], v[72:73], v[54:55] op_sel_hi:[1,0]
	v_pk_mul_f32 v[38:39], v[6:7], v[48:49] op_sel:[0,1] op_sel_hi:[1,1]
	v_pk_fma_f32 v[10:11], v[10:11], v[66:67], v[42:43] op_sel:[0,0,0] op_sel_hi:[1,0,1]
	s_waitcnt lgkmcnt(1)
	v_pk_mul_f32 v[42:43], v[72:73], v[56:57] op_sel_hi:[1,0]
	v_pk_fma_f32 v[38:39], v[8:9], v[50:51], v[38:39] op_sel:[0,1,0] op_sel_hi:[1,1,1]
	v_pk_fma_f32 v[12:13], v[12:13], v[66:67], v[44:45] op_sel:[0,1,0] op_sel_hi:[1,1,1]
	v_pk_mul_f32 v[44:45], v[72:73], v[58:59] op_sel_hi:[1,0]
	v_pk_fma_f32 v[38:39], v[10:11], v[52:53], v[38:39] op_sel:[0,1,0] op_sel_hi:[1,1,1]
	v_pk_fma_f32 v[14:15], v[14:15], v[68:69], v[42:43] op_sel:[0,0,0] op_sel_hi:[1,0,1]
	s_waitcnt lgkmcnt(0)
	v_pk_mul_f32 v[42:43], v[72:73], v[60:61] op_sel_hi:[1,0]
	v_pk_fma_f32 v[38:39], v[12:13], v[54:55], v[38:39] op_sel:[0,1,0] op_sel_hi:[1,1,1]
	v_pk_fma_f32 v[16:17], v[16:17], v[68:69], v[44:45] op_sel:[0,1,0] op_sel_hi:[1,1,1]
	v_pk_mul_f32 v[44:45], v[72:73], v[62:63] op_sel_hi:[1,0]
	v_pk_fma_f32 v[38:39], v[14:15], v[56:57], v[38:39] op_sel:[0,1,0] op_sel_hi:[1,1,1]
	v_pk_fma_f32 v[18:19], v[18:19], v[70:71], v[42:43] op_sel:[0,0,0] op_sel_hi:[1,0,1]
	v_pk_fma_f32 v[38:39], v[16:17], v[58:59], v[38:39] op_sel:[0,1,0] op_sel_hi:[1,1,1]
	v_pk_fma_f32 v[20:21], v[20:21], v[70:71], v[44:45] op_sel:[0,1,0] op_sel_hi:[1,1,1]
	v_pk_fma_f32 v[38:39], v[18:19], v[60:61], v[38:39] op_sel:[0,1,0] op_sel_hi:[1,1,1]
	v_pk_fma_f32 v[38:39], v[20:21], v[62:63], v[38:39] op_sel:[0,1,0] op_sel_hi:[1,1,1]
	s_add_u32 s14, s14, 0x1000
	s_addc_u32 s15, s15, 0
	v_add_f32_dpp v38, v38, v38 row_ror:8 row_mask:0xf bank_mask:0x3 bound_ctrl:1
	v_add_f32_dpp v38, v39, v39 row_ror:8 row_mask:0xf bank_mask:0xc bound_ctrl:1
	ds_read_b64 v[104:105], v3 offset:45568
	ds_read_b128 v[80:83], v2 offset:25856
	v_add_f32_dpp v38, v38, v38 row_half_mirror row_mask:0xf bank_mask:0xf bound_ctrl:1
	ds_read_b128 v[96:99], v2 offset:41728
	ds_read_b128 v[84:87], v2 offset:26112
	v_add_f32_dpp v38, v38, v38 quad_perm:[1,0,3,2] row_mask:0xf bank_mask:0xf bound_ctrl:1
	ds_read_b128 v[88:91], v2 offset:26368
	ds_read_b128 v[100:103], v2 offset:41984
	v_add_f32_dpp v38, v38, v38 quad_perm:[2,3,0,1] row_mask:0xf bank_mask:0xf bound_ctrl:1
	ds_read_b128 v[92:95], v2 offset:26624
	v_cvt_pk_bf16_f32 v47, v38, v38
	s_mov_b64 exec, s[2:3]
	global_store_short v28, v47, s[14:15] offset:-4096
	s_mov_b64 exec, -1
	s_waitcnt lgkmcnt(4)
	v_pk_mul_f32 v[42:43], v[104:105], v[80:81] op_sel_hi:[1,0]
	v_pk_mul_f32 v[44:45], v[104:105], v[82:83] op_sel_hi:[1,0]
	v_pk_fma_f32 v[6:7], v[6:7], v[96:97], v[42:43] op_sel:[0,0,0] op_sel_hi:[1,0,1]
	s_waitcnt lgkmcnt(3)
	v_pk_mul_f32 v[42:43], v[104:105], v[84:85] op_sel_hi:[1,0]
	v_pk_fma_f32 v[8:9], v[8:9], v[96:97], v[44:45] op_sel:[0,1,0] op_sel_hi:[1,1,1]
	v_pk_mul_f32 v[44:45], v[104:105], v[86:87] op_sel_hi:[1,0]
	v_pk_mul_f32 v[38:39], v[6:7], v[80:81] op_sel:[0,1] op_sel_hi:[1,1]
	v_pk_fma_f32 v[10:11], v[10:11], v[98:99], v[42:43] op_sel:[0,0,0] op_sel_hi:[1,0,1]
	s_waitcnt lgkmcnt(1)
	v_pk_mul_f32 v[42:43], v[104:105], v[88:89] op_sel_hi:[1,0]
	v_pk_fma_f32 v[38:39], v[8:9], v[82:83], v[38:39] op_sel:[0,1,0] op_sel_hi:[1,1,1]
	v_pk_fma_f32 v[12:13], v[12:13], v[98:99], v[44:45] op_sel:[0,1,0] op_sel_hi:[1,1,1]
	v_pk_mul_f32 v[44:45], v[104:105], v[90:91] op_sel_hi:[1,0]
	v_pk_fma_f32 v[38:39], v[10:11], v[84:85], v[38:39] op_sel:[0,1,0] op_sel_hi:[1,1,1]
	v_pk_fma_f32 v[14:15], v[14:15], v[100:101], v[42:43] op_sel:[0,0,0] op_sel_hi:[1,0,1]
	s_waitcnt lgkmcnt(0)
	v_pk_mul_f32 v[42:43], v[104:105], v[92:93] op_sel_hi:[1,0]
	v_pk_fma_f32 v[38:39], v[12:13], v[86:87], v[38:39] op_sel:[0,1,0] op_sel_hi:[1,1,1]
	v_pk_fma_f32 v[16:17], v[16:17], v[100:101], v[44:45] op_sel:[0,1,0] op_sel_hi:[1,1,1]
	v_pk_mul_f32 v[44:45], v[104:105], v[94:95] op_sel_hi:[1,0]
	v_pk_fma_f32 v[38:39], v[14:15], v[88:89], v[38:39] op_sel:[0,1,0] op_sel_hi:[1,1,1]
	v_pk_fma_f32 v[18:19], v[18:19], v[102:103], v[42:43] op_sel:[0,0,0] op_sel_hi:[1,0,1]
	v_pk_fma_f32 v[38:39], v[16:17], v[90:91], v[38:39] op_sel:[0,1,0] op_sel_hi:[1,1,1]
	v_pk_fma_f32 v[20:21], v[20:21], v[102:103], v[44:45] op_sel:[0,1,0] op_sel_hi:[1,1,1]
	v_pk_fma_f32 v[38:39], v[18:19], v[92:93], v[38:39] op_sel:[0,1,0] op_sel_hi:[1,1,1]
	v_pk_fma_f32 v[38:39], v[20:21], v[94:95], v[38:39] op_sel:[0,1,0] op_sel_hi:[1,1,1]
	s_add_u32 s14, s14, 0x1000
	s_addc_u32 s15, s15, 0
	v_add_f32_dpp v38, v38, v38 row_ror:8 row_mask:0xf bank_mask:0x3 bound_ctrl:1
	v_add_f32_dpp v38, v39, v39 row_ror:8 row_mask:0xf bank_mask:0xc bound_ctrl:1
	ds_read_b64 v[72:73], v3 offset:45824
	ds_read_b128 v[48:51], v2 offset:26880
	v_add_f32_dpp v38, v38, v38 row_half_mirror row_mask:0xf bank_mask:0xf bound_ctrl:1
	ds_read_b128 v[64:67], v2 offset:42240
	ds_read_b128 v[52:55], v2 offset:27136
	v_add_f32_dpp v38, v38, v38 quad_perm:[1,0,3,2] row_mask:0xf bank_mask:0xf bound_ctrl:1
	ds_read_b128 v[56:59], v2 offset:27392
	ds_read_b128 v[68:71], v2 offset:42496
	v_add_f32_dpp v38, v38, v38 quad_perm:[2,3,0,1] row_mask:0xf bank_mask:0xf bound_ctrl:1
	ds_read_b128 v[60:63], v2 offset:27648
	v_cvt_pk_bf16_f32 v47, v38, v38
	s_mov_b64 exec, s[2:3]
	global_store_short v28, v47, s[14:15] offset:-4096
	s_mov_b64 exec, -1
	s_waitcnt lgkmcnt(4)
	v_pk_mul_f32 v[42:43], v[72:73], v[48:49] op_sel_hi:[1,0]
	v_pk_mul_f32 v[44:45], v[72:73], v[50:51] op_sel_hi:[1,0]
	v_pk_fma_f32 v[6:7], v[6:7], v[64:65], v[42:43] op_sel:[0,0,0] op_sel_hi:[1,0,1]
	s_waitcnt lgkmcnt(3)
	v_pk_mul_f32 v[42:43], v[72:73], v[52:53] op_sel_hi:[1,0]
	v_pk_fma_f32 v[8:9], v[8:9], v[64:65], v[44:45] op_sel:[0,1,0] op_sel_hi:[1,1,1]
	v_pk_mul_f32 v[44:45], v[72:73], v[54:55] op_sel_hi:[1,0]
	v_pk_mul_f32 v[38:39], v[6:7], v[48:49] op_sel:[0,1] op_sel_hi:[1,1]
	v_pk_fma_f32 v[10:11], v[10:11], v[66:67], v[42:43] op_sel:[0,0,0] op_sel_hi:[1,0,1]
	s_waitcnt lgkmcnt(1)
	v_pk_mul_f32 v[42:43], v[72:73], v[56:57] op_sel_hi:[1,0]
	v_pk_fma_f32 v[38:39], v[8:9], v[50:51], v[38:39] op_sel:[0,1,0] op_sel_hi:[1,1,1]
	v_pk_fma_f32 v[12:13], v[12:13], v[66:67], v[44:45] op_sel:[0,1,0] op_sel_hi:[1,1,1]
	v_pk_mul_f32 v[44:45], v[72:73], v[58:59] op_sel_hi:[1,0]
	v_pk_fma_f32 v[38:39], v[10:11], v[52:53], v[38:39] op_sel:[0,1,0] op_sel_hi:[1,1,1]
	v_pk_fma_f32 v[14:15], v[14:15], v[68:69], v[42:43] op_sel:[0,0,0] op_sel_hi:[1,0,1]
	s_waitcnt lgkmcnt(0)
	v_pk_mul_f32 v[42:43], v[72:73], v[60:61] op_sel_hi:[1,0]
	v_pk_fma_f32 v[38:39], v[12:13], v[54:55], v[38:39] op_sel:[0,1,0] op_sel_hi:[1,1,1]
	v_pk_fma_f32 v[16:17], v[16:17], v[68:69], v[44:45] op_sel:[0,1,0] op_sel_hi:[1,1,1]
	v_pk_mul_f32 v[44:45], v[72:73], v[62:63] op_sel_hi:[1,0]
	v_pk_fma_f32 v[38:39], v[14:15], v[56:57], v[38:39] op_sel:[0,1,0] op_sel_hi:[1,1,1]
	v_pk_fma_f32 v[18:19], v[18:19], v[70:71], v[42:43] op_sel:[0,0,0] op_sel_hi:[1,0,1]
	v_pk_fma_f32 v[38:39], v[16:17], v[58:59], v[38:39] op_sel:[0,1,0] op_sel_hi:[1,1,1]
	v_pk_fma_f32 v[20:21], v[20:21], v[70:71], v[44:45] op_sel:[0,1,0] op_sel_hi:[1,1,1]
	v_pk_fma_f32 v[38:39], v[18:19], v[60:61], v[38:39] op_sel:[0,1,0] op_sel_hi:[1,1,1]
	v_pk_fma_f32 v[38:39], v[20:21], v[62:63], v[38:39] op_sel:[0,1,0] op_sel_hi:[1,1,1]
	s_add_u32 s14, s14, 0x1000
	s_addc_u32 s15, s15, 0
	v_add_f32_dpp v38, v38, v38 row_ror:8 row_mask:0xf bank_mask:0x3 bound_ctrl:1
	v_add_f32_dpp v38, v39, v39 row_ror:8 row_mask:0xf bank_mask:0xc bound_ctrl:1
	ds_read_b64 v[104:105], v3 offset:46080
	ds_read_b128 v[80:83], v2 offset:27904
	v_add_f32_dpp v38, v38, v38 row_half_mirror row_mask:0xf bank_mask:0xf bound_ctrl:1
	ds_read_b128 v[96:99], v2 offset:42752
	ds_read_b128 v[84:87], v2 offset:28160
	v_add_f32_dpp v38, v38, v38 quad_perm:[1,0,3,2] row_mask:0xf bank_mask:0xf bound_ctrl:1
	ds_read_b128 v[88:91], v2 offset:28416
	ds_read_b128 v[100:103], v2 offset:43008
	v_add_f32_dpp v38, v38, v38 quad_perm:[2,3,0,1] row_mask:0xf bank_mask:0xf bound_ctrl:1
	ds_read_b128 v[92:95], v2 offset:28672
	v_cvt_pk_bf16_f32 v47, v38, v38
	s_mov_b64 exec, s[2:3]
	global_store_short v28, v47, s[14:15] offset:-4096
	s_mov_b64 exec, -1
	s_waitcnt lgkmcnt(4)
	v_pk_mul_f32 v[42:43], v[104:105], v[80:81] op_sel_hi:[1,0]
	v_pk_mul_f32 v[44:45], v[104:105], v[82:83] op_sel_hi:[1,0]
	v_pk_fma_f32 v[6:7], v[6:7], v[96:97], v[42:43] op_sel:[0,0,0] op_sel_hi:[1,0,1]
	s_waitcnt lgkmcnt(3)
	v_pk_mul_f32 v[42:43], v[104:105], v[84:85] op_sel_hi:[1,0]
	v_pk_fma_f32 v[8:9], v[8:9], v[96:97], v[44:45] op_sel:[0,1,0] op_sel_hi:[1,1,1]
	v_pk_mul_f32 v[44:45], v[104:105], v[86:87] op_sel_hi:[1,0]
	v_pk_mul_f32 v[38:39], v[6:7], v[80:81] op_sel:[0,1] op_sel_hi:[1,1]
	v_pk_fma_f32 v[10:11], v[10:11], v[98:99], v[42:43] op_sel:[0,0,0] op_sel_hi:[1,0,1]
	s_waitcnt lgkmcnt(1)
	v_pk_mul_f32 v[42:43], v[104:105], v[88:89] op_sel_hi:[1,0]
	v_pk_fma_f32 v[38:39], v[8:9], v[82:83], v[38:39] op_sel:[0,1,0] op_sel_hi:[1,1,1]
	v_pk_fma_f32 v[12:13], v[12:13], v[98:99], v[44:45] op_sel:[0,1,0] op_sel_hi:[1,1,1]
	v_pk_mul_f32 v[44:45], v[104:105], v[90:91] op_sel_hi:[1,0]
	v_pk_fma_f32 v[38:39], v[10:11], v[84:85], v[38:39] op_sel:[0,1,0] op_sel_hi:[1,1,1]
	v_pk_fma_f32 v[14:15], v[14:15], v[100:101], v[42:43] op_sel:[0,0,0] op_sel_hi:[1,0,1]
	s_waitcnt lgkmcnt(0)
	v_pk_mul_f32 v[42:43], v[104:105], v[92:93] op_sel_hi:[1,0]
	v_pk_fma_f32 v[38:39], v[12:13], v[86:87], v[38:39] op_sel:[0,1,0] op_sel_hi:[1,1,1]
	v_pk_fma_f32 v[16:17], v[16:17], v[100:101], v[44:45] op_sel:[0,1,0] op_sel_hi:[1,1,1]
	v_pk_mul_f32 v[44:45], v[104:105], v[94:95] op_sel_hi:[1,0]
	v_pk_fma_f32 v[38:39], v[14:15], v[88:89], v[38:39] op_sel:[0,1,0] op_sel_hi:[1,1,1]
	v_pk_fma_f32 v[18:19], v[18:19], v[102:103], v[42:43] op_sel:[0,0,0] op_sel_hi:[1,0,1]
	v_pk_fma_f32 v[38:39], v[16:17], v[90:91], v[38:39] op_sel:[0,1,0] op_sel_hi:[1,1,1]
	v_pk_fma_f32 v[20:21], v[20:21], v[102:103], v[44:45] op_sel:[0,1,0] op_sel_hi:[1,1,1]
	v_pk_fma_f32 v[38:39], v[18:19], v[92:93], v[38:39] op_sel:[0,1,0] op_sel_hi:[1,1,1]
	v_pk_fma_f32 v[38:39], v[20:21], v[94:95], v[38:39] op_sel:[0,1,0] op_sel_hi:[1,1,1]
	s_add_u32 s14, s14, 0x1000
	s_addc_u32 s15, s15, 0
	v_add_f32_dpp v38, v38, v38 row_ror:8 row_mask:0xf bank_mask:0x3 bound_ctrl:1
	v_add_f32_dpp v38, v39, v39 row_ror:8 row_mask:0xf bank_mask:0xc bound_ctrl:1
	ds_read_b64 v[72:73], v3 offset:46336
	ds_read_b128 v[48:51], v2 offset:28928
	v_add_f32_dpp v38, v38, v38 row_half_mirror row_mask:0xf bank_mask:0xf bound_ctrl:1
	ds_read_b128 v[64:67], v2 offset:43264
	ds_read_b128 v[52:55], v2 offset:29184
	v_add_f32_dpp v38, v38, v38 quad_perm:[1,0,3,2] row_mask:0xf bank_mask:0xf bound_ctrl:1
	ds_read_b128 v[56:59], v2 offset:29440
	ds_read_b128 v[68:71], v2 offset:43520
	v_add_f32_dpp v38, v38, v38 quad_perm:[2,3,0,1] row_mask:0xf bank_mask:0xf bound_ctrl:1
	ds_read_b128 v[60:63], v2 offset:29696
	v_cvt_pk_bf16_f32 v47, v38, v38
	s_mov_b64 exec, s[2:3]
	global_store_short v28, v47, s[14:15] offset:-4096
	s_mov_b64 exec, -1
	s_waitcnt lgkmcnt(4)
	v_pk_mul_f32 v[42:43], v[72:73], v[48:49] op_sel_hi:[1,0]
	v_pk_mul_f32 v[44:45], v[72:73], v[50:51] op_sel_hi:[1,0]
	v_pk_fma_f32 v[6:7], v[6:7], v[64:65], v[42:43] op_sel:[0,0,0] op_sel_hi:[1,0,1]
	s_waitcnt lgkmcnt(3)
	v_pk_mul_f32 v[42:43], v[72:73], v[52:53] op_sel_hi:[1,0]
	v_pk_fma_f32 v[8:9], v[8:9], v[64:65], v[44:45] op_sel:[0,1,0] op_sel_hi:[1,1,1]
	v_pk_mul_f32 v[44:45], v[72:73], v[54:55] op_sel_hi:[1,0]
	v_pk_mul_f32 v[38:39], v[6:7], v[48:49] op_sel:[0,1] op_sel_hi:[1,1]
	v_pk_fma_f32 v[10:11], v[10:11], v[66:67], v[42:43] op_sel:[0,0,0] op_sel_hi:[1,0,1]
	s_waitcnt lgkmcnt(1)
	v_pk_mul_f32 v[42:43], v[72:73], v[56:57] op_sel_hi:[1,0]
	v_pk_fma_f32 v[38:39], v[8:9], v[50:51], v[38:39] op_sel:[0,1,0] op_sel_hi:[1,1,1]
	v_pk_fma_f32 v[12:13], v[12:13], v[66:67], v[44:45] op_sel:[0,1,0] op_sel_hi:[1,1,1]
	v_pk_mul_f32 v[44:45], v[72:73], v[58:59] op_sel_hi:[1,0]
	v_pk_fma_f32 v[38:39], v[10:11], v[52:53], v[38:39] op_sel:[0,1,0] op_sel_hi:[1,1,1]
	v_pk_fma_f32 v[14:15], v[14:15], v[68:69], v[42:43] op_sel:[0,0,0] op_sel_hi:[1,0,1]
	s_waitcnt lgkmcnt(0)
	v_pk_mul_f32 v[42:43], v[72:73], v[60:61] op_sel_hi:[1,0]
	v_pk_fma_f32 v[38:39], v[12:13], v[54:55], v[38:39] op_sel:[0,1,0] op_sel_hi:[1,1,1]
	v_pk_fma_f32 v[16:17], v[16:17], v[68:69], v[44:45] op_sel:[0,1,0] op_sel_hi:[1,1,1]
	v_pk_mul_f32 v[44:45], v[72:73], v[62:63] op_sel_hi:[1,0]
	v_pk_fma_f32 v[38:39], v[14:15], v[56:57], v[38:39] op_sel:[0,1,0] op_sel_hi:[1,1,1]
	v_pk_fma_f32 v[18:19], v[18:19], v[70:71], v[42:43] op_sel:[0,0,0] op_sel_hi:[1,0,1]
	v_pk_fma_f32 v[38:39], v[16:17], v[58:59], v[38:39] op_sel:[0,1,0] op_sel_hi:[1,1,1]
	v_pk_fma_f32 v[20:21], v[20:21], v[70:71], v[44:45] op_sel:[0,1,0] op_sel_hi:[1,1,1]
	v_pk_fma_f32 v[38:39], v[18:19], v[60:61], v[38:39] op_sel:[0,1,0] op_sel_hi:[1,1,1]
	v_pk_fma_f32 v[38:39], v[20:21], v[62:63], v[38:39] op_sel:[0,1,0] op_sel_hi:[1,1,1]
	s_add_u32 s14, s14, 0x1000
	s_addc_u32 s15, s15, 0
	v_add_f32_dpp v38, v38, v38 row_ror:8 row_mask:0xf bank_mask:0x3 bound_ctrl:1
	v_add_f32_dpp v38, v39, v39 row_ror:8 row_mask:0xf bank_mask:0xc bound_ctrl:1
	ds_read_b64 v[104:105], v3 offset:46592
	ds_read_b128 v[80:83], v2 offset:29952
	v_add_f32_dpp v38, v38, v38 row_half_mirror row_mask:0xf bank_mask:0xf bound_ctrl:1
	ds_read_b128 v[96:99], v2 offset:43776
	ds_read_b128 v[84:87], v2 offset:30208
	v_add_f32_dpp v38, v38, v38 quad_perm:[1,0,3,2] row_mask:0xf bank_mask:0xf bound_ctrl:1
	ds_read_b128 v[88:91], v2 offset:30464
	ds_read_b128 v[100:103], v2 offset:44032
	v_add_f32_dpp v38, v38, v38 quad_perm:[2,3,0,1] row_mask:0xf bank_mask:0xf bound_ctrl:1
	ds_read_b128 v[92:95], v2 offset:30720
	v_cvt_pk_bf16_f32 v47, v38, v38
	s_mov_b64 exec, s[2:3]
	global_store_short v28, v47, s[14:15] offset:-4096
	s_mov_b64 exec, -1
	s_waitcnt lgkmcnt(4)
	v_pk_mul_f32 v[42:43], v[104:105], v[80:81] op_sel_hi:[1,0]
	v_pk_mul_f32 v[44:45], v[104:105], v[82:83] op_sel_hi:[1,0]
	v_pk_fma_f32 v[6:7], v[6:7], v[96:97], v[42:43] op_sel:[0,0,0] op_sel_hi:[1,0,1]
	s_waitcnt lgkmcnt(3)
	v_pk_mul_f32 v[42:43], v[104:105], v[84:85] op_sel_hi:[1,0]
	v_pk_fma_f32 v[8:9], v[8:9], v[96:97], v[44:45] op_sel:[0,1,0] op_sel_hi:[1,1,1]
	v_pk_mul_f32 v[44:45], v[104:105], v[86:87] op_sel_hi:[1,0]
	v_pk_mul_f32 v[38:39], v[6:7], v[80:81] op_sel:[0,1] op_sel_hi:[1,1]
	v_pk_fma_f32 v[10:11], v[10:11], v[98:99], v[42:43] op_sel:[0,0,0] op_sel_hi:[1,0,1]
	s_waitcnt lgkmcnt(1)
	v_pk_mul_f32 v[42:43], v[104:105], v[88:89] op_sel_hi:[1,0]
	v_pk_fma_f32 v[38:39], v[8:9], v[82:83], v[38:39] op_sel:[0,1,0] op_sel_hi:[1,1,1]
	v_pk_fma_f32 v[12:13], v[12:13], v[98:99], v[44:45] op_sel:[0,1,0] op_sel_hi:[1,1,1]
	v_pk_mul_f32 v[44:45], v[104:105], v[90:91] op_sel_hi:[1,0]
	v_pk_fma_f32 v[38:39], v[10:11], v[84:85], v[38:39] op_sel:[0,1,0] op_sel_hi:[1,1,1]
	v_pk_fma_f32 v[14:15], v[14:15], v[100:101], v[42:43] op_sel:[0,0,0] op_sel_hi:[1,0,1]
	s_waitcnt lgkmcnt(0)
	v_pk_mul_f32 v[42:43], v[104:105], v[92:93] op_sel_hi:[1,0]
	v_pk_fma_f32 v[38:39], v[12:13], v[86:87], v[38:39] op_sel:[0,1,0] op_sel_hi:[1,1,1]
	v_pk_fma_f32 v[16:17], v[16:17], v[100:101], v[44:45] op_sel:[0,1,0] op_sel_hi:[1,1,1]
	v_pk_mul_f32 v[44:45], v[104:105], v[94:95] op_sel_hi:[1,0]
	v_pk_fma_f32 v[38:39], v[14:15], v[88:89], v[38:39] op_sel:[0,1,0] op_sel_hi:[1,1,1]
	v_pk_fma_f32 v[18:19], v[18:19], v[102:103], v[42:43] op_sel:[0,0,0] op_sel_hi:[1,0,1]
	v_pk_fma_f32 v[38:39], v[16:17], v[90:91], v[38:39] op_sel:[0,1,0] op_sel_hi:[1,1,1]
	v_pk_fma_f32 v[20:21], v[20:21], v[102:103], v[44:45] op_sel:[0,1,0] op_sel_hi:[1,1,1]
	v_pk_fma_f32 v[38:39], v[18:19], v[92:93], v[38:39] op_sel:[0,1,0] op_sel_hi:[1,1,1]
	v_pk_fma_f32 v[38:39], v[20:21], v[94:95], v[38:39] op_sel:[0,1,0] op_sel_hi:[1,1,1]
	s_add_u32 s14, s14, 0x1000
	s_addc_u32 s15, s15, 0
	v_add_f32_dpp v38, v38, v38 row_ror:8 row_mask:0xf bank_mask:0x3 bound_ctrl:1
	v_add_f32_dpp v38, v39, v39 row_ror:8 row_mask:0xf bank_mask:0xc bound_ctrl:1
	ds_read_b64 v[72:73], v3 offset:46848
	ds_read_b128 v[48:51], v2 offset:30976
	v_add_f32_dpp v38, v38, v38 row_half_mirror row_mask:0xf bank_mask:0xf bound_ctrl:1
	ds_read_b128 v[64:67], v2 offset:44288
	ds_read_b128 v[52:55], v2 offset:31232
	v_add_f32_dpp v38, v38, v38 quad_perm:[1,0,3,2] row_mask:0xf bank_mask:0xf bound_ctrl:1
	ds_read_b128 v[56:59], v2 offset:31488
	ds_read_b128 v[68:71], v2 offset:44544
	v_add_f32_dpp v38, v38, v38 quad_perm:[2,3,0,1] row_mask:0xf bank_mask:0xf bound_ctrl:1
	ds_read_b128 v[60:63], v2 offset:31744
	v_cvt_pk_bf16_f32 v47, v38, v38
	s_mov_b64 exec, s[2:3]
	global_store_short v28, v47, s[14:15] offset:-4096
	s_mov_b64 exec, -1
	s_waitcnt lgkmcnt(4)
	v_pk_mul_f32 v[42:43], v[72:73], v[48:49] op_sel_hi:[1,0]
	v_pk_mul_f32 v[44:45], v[72:73], v[50:51] op_sel_hi:[1,0]
	v_pk_fma_f32 v[6:7], v[6:7], v[64:65], v[42:43] op_sel:[0,0,0] op_sel_hi:[1,0,1]
	s_waitcnt lgkmcnt(3)
	v_pk_mul_f32 v[42:43], v[72:73], v[52:53] op_sel_hi:[1,0]
	v_pk_fma_f32 v[8:9], v[8:9], v[64:65], v[44:45] op_sel:[0,1,0] op_sel_hi:[1,1,1]
	v_pk_mul_f32 v[44:45], v[72:73], v[54:55] op_sel_hi:[1,0]
	v_pk_mul_f32 v[38:39], v[6:7], v[48:49] op_sel:[0,1] op_sel_hi:[1,1]
	v_pk_fma_f32 v[10:11], v[10:11], v[66:67], v[42:43] op_sel:[0,0,0] op_sel_hi:[1,0,1]
	s_waitcnt lgkmcnt(1)
	v_pk_mul_f32 v[42:43], v[72:73], v[56:57] op_sel_hi:[1,0]
	v_pk_fma_f32 v[38:39], v[8:9], v[50:51], v[38:39] op_sel:[0,1,0] op_sel_hi:[1,1,1]
	v_pk_fma_f32 v[12:13], v[12:13], v[66:67], v[44:45] op_sel:[0,1,0] op_sel_hi:[1,1,1]
	v_pk_mul_f32 v[44:45], v[72:73], v[58:59] op_sel_hi:[1,0]
	v_pk_fma_f32 v[38:39], v[10:11], v[52:53], v[38:39] op_sel:[0,1,0] op_sel_hi:[1,1,1]
	v_pk_fma_f32 v[14:15], v[14:15], v[68:69], v[42:43] op_sel:[0,0,0] op_sel_hi:[1,0,1]
	s_waitcnt lgkmcnt(0)
	v_pk_mul_f32 v[42:43], v[72:73], v[60:61] op_sel_hi:[1,0]
	v_pk_fma_f32 v[38:39], v[12:13], v[54:55], v[38:39] op_sel:[0,1,0] op_sel_hi:[1,1,1]
	v_pk_fma_f32 v[16:17], v[16:17], v[68:69], v[44:45] op_sel:[0,1,0] op_sel_hi:[1,1,1]
	v_pk_mul_f32 v[44:45], v[72:73], v[62:63] op_sel_hi:[1,0]
	v_pk_fma_f32 v[38:39], v[14:15], v[56:57], v[38:39] op_sel:[0,1,0] op_sel_hi:[1,1,1]
	v_pk_fma_f32 v[18:19], v[18:19], v[70:71], v[42:43] op_sel:[0,0,0] op_sel_hi:[1,0,1]
	v_pk_fma_f32 v[38:39], v[16:17], v[58:59], v[38:39] op_sel:[0,1,0] op_sel_hi:[1,1,1]
	v_pk_fma_f32 v[20:21], v[20:21], v[70:71], v[44:45] op_sel:[0,1,0] op_sel_hi:[1,1,1]
	v_pk_fma_f32 v[38:39], v[18:19], v[60:61], v[38:39] op_sel:[0,1,0] op_sel_hi:[1,1,1]
	v_pk_fma_f32 v[38:39], v[20:21], v[62:63], v[38:39] op_sel:[0,1,0] op_sel_hi:[1,1,1]
	s_add_u32 s14, s14, 0x1000
	s_addc_u32 s15, s15, 0
	v_add_f32_dpp v38, v38, v38 row_ror:8 row_mask:0xf bank_mask:0x3 bound_ctrl:1
	v_add_f32_dpp v38, v39, v39 row_ror:8 row_mask:0xf bank_mask:0xc bound_ctrl:1
	ds_read_b64 v[104:105], v3 offset:47104
	ds_read_b128 v[80:83], v2 offset:32000
	v_add_f32_dpp v38, v38, v38 row_half_mirror row_mask:0xf bank_mask:0xf bound_ctrl:1
	ds_read_b128 v[96:99], v2 offset:44800
	ds_read_b128 v[84:87], v2 offset:32256
	v_add_f32_dpp v38, v38, v38 quad_perm:[1,0,3,2] row_mask:0xf bank_mask:0xf bound_ctrl:1
	ds_read_b128 v[88:91], v2 offset:32512
	ds_read_b128 v[100:103], v2 offset:45056
	v_add_f32_dpp v38, v38, v38 quad_perm:[2,3,0,1] row_mask:0xf bank_mask:0xf bound_ctrl:1
	ds_read_b128 v[92:95], v2 offset:32768
	v_cvt_pk_bf16_f32 v47, v38, v38
	s_mov_b64 exec, s[2:3]
	global_store_short v28, v47, s[14:15] offset:-4096
	s_mov_b64 exec, -1
	s_waitcnt lgkmcnt(4)
	v_pk_mul_f32 v[42:43], v[104:105], v[80:81] op_sel_hi:[1,0]
	v_pk_mul_f32 v[44:45], v[104:105], v[82:83] op_sel_hi:[1,0]
	v_pk_fma_f32 v[6:7], v[6:7], v[96:97], v[42:43] op_sel:[0,0,0] op_sel_hi:[1,0,1]
	s_waitcnt lgkmcnt(3)
	v_pk_mul_f32 v[42:43], v[104:105], v[84:85] op_sel_hi:[1,0]
	v_pk_fma_f32 v[8:9], v[8:9], v[96:97], v[44:45] op_sel:[0,1,0] op_sel_hi:[1,1,1]
	v_pk_mul_f32 v[44:45], v[104:105], v[86:87] op_sel_hi:[1,0]
	v_pk_mul_f32 v[38:39], v[6:7], v[80:81] op_sel:[0,1] op_sel_hi:[1,1]
	v_pk_fma_f32 v[10:11], v[10:11], v[98:99], v[42:43] op_sel:[0,0,0] op_sel_hi:[1,0,1]
	s_waitcnt lgkmcnt(1)
	v_pk_mul_f32 v[42:43], v[104:105], v[88:89] op_sel_hi:[1,0]
	v_pk_fma_f32 v[38:39], v[8:9], v[82:83], v[38:39] op_sel:[0,1,0] op_sel_hi:[1,1,1]
	v_pk_fma_f32 v[12:13], v[12:13], v[98:99], v[44:45] op_sel:[0,1,0] op_sel_hi:[1,1,1]
	v_pk_mul_f32 v[44:45], v[104:105], v[90:91] op_sel_hi:[1,0]
	v_pk_fma_f32 v[38:39], v[10:11], v[84:85], v[38:39] op_sel:[0,1,0] op_sel_hi:[1,1,1]
	v_pk_fma_f32 v[14:15], v[14:15], v[100:101], v[42:43] op_sel:[0,0,0] op_sel_hi:[1,0,1]
	s_waitcnt lgkmcnt(0)
	v_pk_mul_f32 v[42:43], v[104:105], v[92:93] op_sel_hi:[1,0]
	v_pk_fma_f32 v[38:39], v[12:13], v[86:87], v[38:39] op_sel:[0,1,0] op_sel_hi:[1,1,1]
	v_pk_fma_f32 v[16:17], v[16:17], v[100:101], v[44:45] op_sel:[0,1,0] op_sel_hi:[1,1,1]
	v_pk_mul_f32 v[44:45], v[104:105], v[94:95] op_sel_hi:[1,0]
	v_pk_fma_f32 v[38:39], v[14:15], v[88:89], v[38:39] op_sel:[0,1,0] op_sel_hi:[1,1,1]
	v_pk_fma_f32 v[18:19], v[18:19], v[102:103], v[42:43] op_sel:[0,0,0] op_sel_hi:[1,0,1]
	v_pk_fma_f32 v[38:39], v[16:17], v[90:91], v[38:39] op_sel:[0,1,0] op_sel_hi:[1,1,1]
	v_pk_fma_f32 v[20:21], v[20:21], v[102:103], v[44:45] op_sel:[0,1,0] op_sel_hi:[1,1,1]
	v_pk_fma_f32 v[38:39], v[18:19], v[92:93], v[38:39] op_sel:[0,1,0] op_sel_hi:[1,1,1]
	v_pk_fma_f32 v[38:39], v[20:21], v[94:95], v[38:39] op_sel:[0,1,0] op_sel_hi:[1,1,1]
	s_add_u32 s14, s14, 0x1000
	s_addc_u32 s15, s15, 0
	v_add_f32_dpp v38, v38, v38 row_ror:8 row_mask:0xf bank_mask:0x3 bound_ctrl:1
	v_add_f32_dpp v38, v39, v39 row_ror:8 row_mask:0xf bank_mask:0xc bound_ctrl:1
	ds_read_b64 v[72:73], v23 offset:37120
	ds_read_b128 v[48:51], v2 offset:49408
	v_add_f32_dpp v38, v38, v38 row_half_mirror row_mask:0xf bank_mask:0xf bound_ctrl:1
	ds_read_b128 v[64:67], v22 offset:33024
	ds_read_b128 v[52:55], v2 offset:49664
	v_add_f32_dpp v38, v38, v38 quad_perm:[1,0,3,2] row_mask:0xf bank_mask:0xf bound_ctrl:1
	ds_read_b128 v[56:59], v2 offset:49920
	ds_read_b128 v[68:71], v22 offset:33280
	v_add_f32_dpp v38, v38, v38 quad_perm:[2,3,0,1] row_mask:0xf bank_mask:0xf bound_ctrl:1
	ds_read_b128 v[60:63], v2 offset:50176
	v_cvt_pk_bf16_f32 v47, v38, v38
	s_mov_b64 exec, s[2:3]
	global_store_short v28, v47, s[14:15] offset:-4096
	s_mov_b64 exec, -1
	s_waitcnt vmcnt(8)
	v_lshlrev_b32_e32 v144, 16, v110
	v_lshlrev_b32_e32 v145, 16, v111
	v_and_b32_e32 v146, s17, v110
	v_and_b32_e32 v147, s17, v111
	v_lshlrev_b32_e32 v148, 16, v112
	v_lshlrev_b32_e32 v149, 16, v113
	v_and_b32_e32 v150, s17, v112
	v_and_b32_e32 v151, s17, v113
	v_lshlrev_b32_e32 v152, 16, v114
	v_and_b32_e32 v153, s17, v114
	v_rcp_f32_e32 v25, v24
	v_mul_f32_e32 v149, v24, v149
	v_mul_f32_e32 v151, v24, v151
	v_mul_f32_e32 v145, 0x3db504f3, v145
	v_mul_f32_e32 v147, 0x3db504f3, v147
	v_cndmask_b32_e64 v27, 1.0, v25, s[20:21]
	v_mul_f32_e32 v24, v24, v26
	v_mul_f32_e32 v152, v27, v152
	v_mul_f32_e32 v153, v27, v153
	ds_write_b128 v29, v[144:147] offset:256
	ds_write_b128 v29, v[148:151] offset:8448
	ds_write_b64 v30, v[116:117] offset:256
	ds_write_b64 v31, v[152:153] offset:256
	s_add_i32 s16, s16, 8
	s_waitcnt lgkmcnt(0)
	s_barrier
	s_cmpk_lt_u32 s16, 0x800
	s_cbranch_scc0 .Lgla2_done
	global_load_dword v110, v32, s[10:11]
	global_load_dword v111, v32, s[10:11] offset:-1024
	global_load_dword v112, v33, s[10:11]
	global_load_dword v113, v33, s[10:11] offset:-1024
	global_load_dword v114, v34, s[10:11]
	global_load_dword v116, v35, s[12:13]
	global_load_dword v117, v35, s[12:13] offset:4
	s_add_u32 s10, s10, 0x18000
	s_addc_u32 s11, s11, 0
	s_add_u32 s12, s12, 0x4000
	s_addc_u32 s13, s13, 0
	s_waitcnt lgkmcnt(4)
	v_pk_mul_f32 v[42:43], v[72:73], v[48:49] op_sel_hi:[1,0]
	v_pk_mul_f32 v[44:45], v[72:73], v[50:51] op_sel_hi:[1,0]
	v_pk_fma_f32 v[6:7], v[6:7], v[64:65], v[42:43] op_sel:[0,0,0] op_sel_hi:[1,0,1]
	s_waitcnt lgkmcnt(3)
	v_pk_mul_f32 v[42:43], v[72:73], v[52:53] op_sel_hi:[1,0]
	v_pk_fma_f32 v[8:9], v[8:9], v[64:65], v[44:45] op_sel:[0,1,0] op_sel_hi:[1,1,1]
	v_pk_mul_f32 v[44:45], v[72:73], v[54:55] op_sel_hi:[1,0]
	v_pk_mul_f32 v[38:39], v[6:7], v[48:49] op_sel:[0,1] op_sel_hi:[1,1]
	v_pk_fma_f32 v[10:11], v[10:11], v[66:67], v[42:43] op_sel:[0,0,0] op_sel_hi:[1,0,1]
	s_waitcnt lgkmcnt(1)
	v_pk_mul_f32 v[42:43], v[72:73], v[56:57] op_sel_hi:[1,0]
	v_pk_fma_f32 v[38:39], v[8:9], v[50:51], v[38:39] op_sel:[0,1,0] op_sel_hi:[1,1,1]
	v_pk_fma_f32 v[12:13], v[12:13], v[66:67], v[44:45] op_sel:[0,1,0] op_sel_hi:[1,1,1]
	v_pk_mul_f32 v[44:45], v[72:73], v[58:59] op_sel_hi:[1,0]
	v_pk_fma_f32 v[38:39], v[10:11], v[52:53], v[38:39] op_sel:[0,1,0] op_sel_hi:[1,1,1]
	v_pk_fma_f32 v[14:15], v[14:15], v[68:69], v[42:43] op_sel:[0,0,0] op_sel_hi:[1,0,1]
	s_waitcnt lgkmcnt(0)
	v_pk_mul_f32 v[42:43], v[72:73], v[60:61] op_sel_hi:[1,0]
	v_pk_fma_f32 v[38:39], v[12:13], v[54:55], v[38:39] op_sel:[0,1,0] op_sel_hi:[1,1,1]
	v_pk_fma_f32 v[16:17], v[16:17], v[68:69], v[44:45] op_sel:[0,1,0] op_sel_hi:[1,1,1]
	v_pk_mul_f32 v[44:45], v[72:73], v[62:63] op_sel_hi:[1,0]
	v_pk_fma_f32 v[38:39], v[14:15], v[56:57], v[38:39] op_sel:[0,1,0] op_sel_hi:[1,1,1]
	v_pk_fma_f32 v[18:19], v[18:19], v[70:71], v[42:43] op_sel:[0,0,0] op_sel_hi:[1,0,1]
	v_pk_fma_f32 v[38:39], v[16:17], v[58:59], v[38:39] op_sel:[0,1,0] op_sel_hi:[1,1,1]
	v_pk_fma_f32 v[20:21], v[20:21], v[70:71], v[44:45] op_sel:[0,1,0] op_sel_hi:[1,1,1]
	v_pk_fma_f32 v[38:39], v[18:19], v[60:61], v[38:39] op_sel:[0,1,0] op_sel_hi:[1,1,1]
	v_pk_fma_f32 v[38:39], v[20:21], v[62:63], v[38:39] op_sel:[0,1,0] op_sel_hi:[1,1,1]
	s_add_u32 s14, s14, 0x1000
	s_addc_u32 s15, s15, 0
	v_add_f32_dpp v38, v38, v38 row_ror:8 row_mask:0xf bank_mask:0x3 bound_ctrl:1
	v_add_f32_dpp v38, v39, v39 row_ror:8 row_mask:0xf bank_mask:0xc bound_ctrl:1
	ds_read_b64 v[104:105], v23 offset:37376
	ds_read_b128 v[80:83], v2 offset:50432
	v_add_f32_dpp v38, v38, v38 row_half_mirror row_mask:0xf bank_mask:0xf bound_ctrl:1
	ds_read_b128 v[96:99], v22 offset:33536
	ds_read_b128 v[84:87], v2 offset:50688
	v_add_f32_dpp v38, v38, v38 quad_perm:[1,0,3,2] row_mask:0xf bank_mask:0xf bound_ctrl:1
	ds_read_b128 v[88:91], v2 offset:50944
	ds_read_b128 v[100:103], v22 offset:33792
	v_add_f32_dpp v38, v38, v38 quad_perm:[2,3,0,1] row_mask:0xf bank_mask:0xf bound_ctrl:1
	ds_read_b128 v[92:95], v2 offset:51200
	v_cvt_pk_bf16_f32 v47, v38, v38
	s_mov_b64 exec, s[2:3]
	global_store_short v28, v47, s[14:15] offset:-4096
	s_mov_b64 exec, -1
	s_waitcnt lgkmcnt(4)
	v_pk_mul_f32 v[42:43], v[104:105], v[80:81] op_sel_hi:[1,0]
	v_pk_mul_f32 v[44:45], v[104:105], v[82:83] op_sel_hi:[1,0]
	v_pk_fma_f32 v[6:7], v[6:7], v[96:97], v[42:43] op_sel:[0,0,0] op_sel_hi:[1,0,1]
	s_waitcnt lgkmcnt(3)
	v_pk_mul_f32 v[42:43], v[104:105], v[84:85] op_sel_hi:[1,0]
	v_pk_fma_f32 v[8:9], v[8:9], v[96:97], v[44:45] op_sel:[0,1,0] op_sel_hi:[1,1,1]
	v_pk_mul_f32 v[44:45], v[104:105], v[86:87] op_sel_hi:[1,0]
	v_pk_mul_f32 v[38:39], v[6:7], v[80:81] op_sel:[0,1] op_sel_hi:[1,1]
	v_pk_fma_f32 v[10:11], v[10:11], v[98:99], v[42:43] op_sel:[0,0,0] op_sel_hi:[1,0,1]
	s_waitcnt lgkmcnt(1)
	v_pk_mul_f32 v[42:43], v[104:105], v[88:89] op_sel_hi:[1,0]
	v_pk_fma_f32 v[38:39], v[8:9], v[82:83], v[38:39] op_sel:[0,1,0] op_sel_hi:[1,1,1]
	v_pk_fma_f32 v[12:13], v[12:13], v[98:99], v[44:45] op_sel:[0,1,0] op_sel_hi:[1,1,1]
	v_pk_mul_f32 v[44:45], v[104:105], v[90:91] op_sel_hi:[1,0]
	v_pk_fma_f32 v[38:39], v[10:11], v[84:85], v[38:39] op_sel:[0,1,0] op_sel_hi:[1,1,1]
	v_pk_fma_f32 v[14:15], v[14:15], v[100:101], v[42:43] op_sel:[0,0,0] op_sel_hi:[1,0,1]
	s_waitcnt lgkmcnt(0)
	v_pk_mul_f32 v[42:43], v[104:105], v[92:93] op_sel_hi:[1,0]
	v_pk_fma_f32 v[38:39], v[12:13], v[86:87], v[38:39] op_sel:[0,1,0] op_sel_hi:[1,1,1]
	v_pk_fma_f32 v[16:17], v[16:17], v[100:101], v[44:45] op_sel:[0,1,0] op_sel_hi:[1,1,1]
	v_pk_mul_f32 v[44:45], v[104:105], v[94:95] op_sel_hi:[1,0]
	v_pk_fma_f32 v[38:39], v[14:15], v[88:89], v[38:39] op_sel:[0,1,0] op_sel_hi:[1,1,1]
	v_pk_fma_f32 v[18:19], v[18:19], v[102:103], v[42:43] op_sel:[0,0,0] op_sel_hi:[1,0,1]
	v_pk_fma_f32 v[38:39], v[16:17], v[90:91], v[38:39] op_sel:[0,1,0] op_sel_hi:[1,1,1]
	v_pk_fma_f32 v[20:21], v[20:21], v[102:103], v[44:45] op_sel:[0,1,0] op_sel_hi:[1,1,1]
	v_pk_fma_f32 v[38:39], v[18:19], v[92:93], v[38:39] op_sel:[0,1,0] op_sel_hi:[1,1,1]
	v_pk_fma_f32 v[38:39], v[20:21], v[94:95], v[38:39] op_sel:[0,1,0] op_sel_hi:[1,1,1]
	s_add_u32 s14, s14, 0x1000
	s_addc_u32 s15, s15, 0
	v_add_f32_dpp v38, v38, v38 row_ror:8 row_mask:0xf bank_mask:0x3 bound_ctrl:1
	v_add_f32_dpp v38, v39, v39 row_ror:8 row_mask:0xf bank_mask:0xc bound_ctrl:1
	ds_read_b64 v[72:73], v23 offset:37632
	ds_read_b128 v[48:51], v2 offset:51456
	v_add_f32_dpp v38, v38, v38 row_half_mirror row_mask:0xf bank_mask:0xf bound_ctrl:1
	ds_read_b128 v[64:67], v22 offset:34048
	ds_read_b128 v[52:55], v2 offset:51712
	v_add_f32_dpp v38, v38, v38 quad_perm:[1,0,3,2] row_mask:0xf bank_mask:0xf bound_ctrl:1
	ds_read_b128 v[56:59], v2 offset:51968
	ds_read_b128 v[68:71], v22 offset:34304
	v_add_f32_dpp v38, v38, v38 quad_perm:[2,3,0,1] row_mask:0xf bank_mask:0xf bound_ctrl:1
	ds_read_b128 v[60:63], v2 offset:52224
	v_cvt_pk_bf16_f32 v47, v38, v38
	s_mov_b64 exec, s[2:3]
	global_store_short v28, v47, s[14:15] offset:-4096
	s_mov_b64 exec, -1
	s_waitcnt lgkmcnt(4)
	v_pk_mul_f32 v[42:43], v[72:73], v[48:49] op_sel_hi:[1,0]
	v_pk_mul_f32 v[44:45], v[72:73], v[50:51] op_sel_hi:[1,0]
	v_pk_fma_f32 v[6:7], v[6:7], v[64:65], v[42:43] op_sel:[0,0,0] op_sel_hi:[1,0,1]
	s_waitcnt lgkmcnt(3)
	v_pk_mul_f32 v[42:43], v[72:73], v[52:53] op_sel_hi:[1,0]
	v_pk_fma_f32 v[8:9], v[8:9], v[64:65], v[44:45] op_sel:[0,1,0] op_sel_hi:[1,1,1]
	v_pk_mul_f32 v[44:45], v[72:73], v[54:55] op_sel_hi:[1,0]
	v_pk_mul_f32 v[38:39], v[6:7], v[48:49] op_sel:[0,1] op_sel_hi:[1,1]
	v_pk_fma_f32 v[10:11], v[10:11], v[66:67], v[42:43] op_sel:[0,0,0] op_sel_hi:[1,0,1]
	s_waitcnt lgkmcnt(1)
	v_pk_mul_f32 v[42:43], v[72:73], v[56:57] op_sel_hi:[1,0]
	v_pk_fma_f32 v[38:39], v[8:9], v[50:51], v[38:39] op_sel:[0,1,0] op_sel_hi:[1,1,1]
	v_pk_fma_f32 v[12:13], v[12:13], v[66:67], v[44:45] op_sel:[0,1,0] op_sel_hi:[1,1,1]
	v_pk_mul_f32 v[44:45], v[72:73], v[58:59] op_sel_hi:[1,0]
	v_pk_fma_f32 v[38:39], v[10:11], v[52:53], v[38:39] op_sel:[0,1,0] op_sel_hi:[1,1,1]
	v_pk_fma_f32 v[14:15], v[14:15], v[68:69], v[42:43] op_sel:[0,0,0] op_sel_hi:[1,0,1]
	s_waitcnt lgkmcnt(0)
	v_pk_mul_f32 v[42:43], v[72:73], v[60:61] op_sel_hi:[1,0]
	v_pk_fma_f32 v[38:39], v[12:13], v[54:55], v[38:39] op_sel:[0,1,0] op_sel_hi:[1,1,1]
	v_pk_fma_f32 v[16:17], v[16:17], v[68:69], v[44:45] op_sel:[0,1,0] op_sel_hi:[1,1,1]
	v_pk_mul_f32 v[44:45], v[72:73], v[62:63] op_sel_hi:[1,0]
	v_pk_fma_f32 v[38:39], v[14:15], v[56:57], v[38:39] op_sel:[0,1,0] op_sel_hi:[1,1,1]
	v_pk_fma_f32 v[18:19], v[18:19], v[70:71], v[42:43] op_sel:[0,0,0] op_sel_hi:[1,0,1]
	v_pk_fma_f32 v[38:39], v[16:17], v[58:59], v[38:39] op_sel:[0,1,0] op_sel_hi:[1,1,1]
	v_pk_fma_f32 v[20:21], v[20:21], v[70:71], v[44:45] op_sel:[0,1,0] op_sel_hi:[1,1,1]
	v_pk_fma_f32 v[38:39], v[18:19], v[60:61], v[38:39] op_sel:[0,1,0] op_sel_hi:[1,1,1]
	v_pk_fma_f32 v[38:39], v[20:21], v[62:63], v[38:39] op_sel:[0,1,0] op_sel_hi:[1,1,1]
	s_add_u32 s14, s14, 0x1000
	s_addc_u32 s15, s15, 0
	v_add_f32_dpp v38, v38, v38 row_ror:8 row_mask:0xf bank_mask:0x3 bound_ctrl:1
	v_add_f32_dpp v38, v39, v39 row_ror:8 row_mask:0xf bank_mask:0xc bound_ctrl:1
	ds_read_b64 v[104:105], v23 offset:37888
	ds_read_b128 v[80:83], v2 offset:52480
	v_add_f32_dpp v38, v38, v38 row_half_mirror row_mask:0xf bank_mask:0xf bound_ctrl:1
	ds_read_b128 v[96:99], v22 offset:34560
	ds_read_b128 v[84:87], v2 offset:52736
	v_add_f32_dpp v38, v38, v38 quad_perm:[1,0,3,2] row_mask:0xf bank_mask:0xf bound_ctrl:1
	ds_read_b128 v[88:91], v2 offset:52992
	ds_read_b128 v[100:103], v22 offset:34816
	v_add_f32_dpp v38, v38, v38 quad_perm:[2,3,0,1] row_mask:0xf bank_mask:0xf bound_ctrl:1
	ds_read_b128 v[92:95], v2 offset:53248
	v_cvt_pk_bf16_f32 v47, v38, v38
	s_mov_b64 exec, s[2:3]
	global_store_short v28, v47, s[14:15] offset:-4096
	s_mov_b64 exec, -1
	s_waitcnt lgkmcnt(4)
	v_pk_mul_f32 v[42:43], v[104:105], v[80:81] op_sel_hi:[1,0]
	v_pk_mul_f32 v[44:45], v[104:105], v[82:83] op_sel_hi:[1,0]
	v_pk_fma_f32 v[6:7], v[6:7], v[96:97], v[42:43] op_sel:[0,0,0] op_sel_hi:[1,0,1]
	s_waitcnt lgkmcnt(3)
	v_pk_mul_f32 v[42:43], v[104:105], v[84:85] op_sel_hi:[1,0]
	v_pk_fma_f32 v[8:9], v[8:9], v[96:97], v[44:45] op_sel:[0,1,0] op_sel_hi:[1,1,1]
	v_pk_mul_f32 v[44:45], v[104:105], v[86:87] op_sel_hi:[1,0]
	v_pk_mul_f32 v[38:39], v[6:7], v[80:81] op_sel:[0,1] op_sel_hi:[1,1]
	v_pk_fma_f32 v[10:11], v[10:11], v[98:99], v[42:43] op_sel:[0,0,0] op_sel_hi:[1,0,1]
	s_waitcnt lgkmcnt(1)
	v_pk_mul_f32 v[42:43], v[104:105], v[88:89] op_sel_hi:[1,0]
	v_pk_fma_f32 v[38:39], v[8:9], v[82:83], v[38:39] op_sel:[0,1,0] op_sel_hi:[1,1,1]
	v_pk_fma_f32 v[12:13], v[12:13], v[98:99], v[44:45] op_sel:[0,1,0] op_sel_hi:[1,1,1]
	v_pk_mul_f32 v[44:45], v[104:105], v[90:91] op_sel_hi:[1,0]
	v_pk_fma_f32 v[38:39], v[10:11], v[84:85], v[38:39] op_sel:[0,1,0] op_sel_hi:[1,1,1]
	v_pk_fma_f32 v[14:15], v[14:15], v[100:101], v[42:43] op_sel:[0,0,0] op_sel_hi:[1,0,1]
	s_waitcnt lgkmcnt(0)
	v_pk_mul_f32 v[42:43], v[104:105], v[92:93] op_sel_hi:[1,0]
	v_pk_fma_f32 v[38:39], v[12:13], v[86:87], v[38:39] op_sel:[0,1,0] op_sel_hi:[1,1,1]
	v_pk_fma_f32 v[16:17], v[16:17], v[100:101], v[44:45] op_sel:[0,1,0] op_sel_hi:[1,1,1]
	v_pk_mul_f32 v[44:45], v[104:105], v[94:95] op_sel_hi:[1,0]
	v_pk_fma_f32 v[38:39], v[14:15], v[88:89], v[38:39] op_sel:[0,1,0] op_sel_hi:[1,1,1]
	v_pk_fma_f32 v[18:19], v[18:19], v[102:103], v[42:43] op_sel:[0,0,0] op_sel_hi:[1,0,1]
	v_pk_fma_f32 v[38:39], v[16:17], v[90:91], v[38:39] op_sel:[0,1,0] op_sel_hi:[1,1,1]
	v_pk_fma_f32 v[20:21], v[20:21], v[102:103], v[44:45] op_sel:[0,1,0] op_sel_hi:[1,1,1]
	v_pk_fma_f32 v[38:39], v[18:19], v[92:93], v[38:39] op_sel:[0,1,0] op_sel_hi:[1,1,1]
	v_pk_fma_f32 v[38:39], v[20:21], v[94:95], v[38:39] op_sel:[0,1,0] op_sel_hi:[1,1,1]
	s_add_u32 s14, s14, 0x1000
	s_addc_u32 s15, s15, 0
	v_add_f32_dpp v38, v38, v38 row_ror:8 row_mask:0xf bank_mask:0x3 bound_ctrl:1
	v_add_f32_dpp v38, v39, v39 row_ror:8 row_mask:0xf bank_mask:0xc bound_ctrl:1
	ds_read_b64 v[72:73], v23 offset:38144
	ds_read_b128 v[48:51], v2 offset:53504
	v_add_f32_dpp v38, v38, v38 row_half_mirror row_mask:0xf bank_mask:0xf bound_ctrl:1
	ds_read_b128 v[64:67], v22 offset:35072
	ds_read_b128 v[52:55], v2 offset:53760
	v_add_f32_dpp v38, v38, v38 quad_perm:[1,0,3,2] row_mask:0xf bank_mask:0xf bound_ctrl:1
	ds_read_b128 v[56:59], v2 offset:54016
	ds_read_b128 v[68:71], v22 offset:35328
	v_add_f32_dpp v38, v38, v38 quad_perm:[2,3,0,1] row_mask:0xf bank_mask:0xf bound_ctrl:1
	ds_read_b128 v[60:63], v2 offset:54272
	v_cvt_pk_bf16_f32 v47, v38, v38
	s_mov_b64 exec, s[2:3]
	global_store_short v28, v47, s[14:15] offset:-4096
	s_mov_b64 exec, -1
	s_waitcnt lgkmcnt(4)
	v_pk_mul_f32 v[42:43], v[72:73], v[48:49] op_sel_hi:[1,0]
	v_pk_mul_f32 v[44:45], v[72:73], v[50:51] op_sel_hi:[1,0]
	v_pk_fma_f32 v[6:7], v[6:7], v[64:65], v[42:43] op_sel:[0,0,0] op_sel_hi:[1,0,1]
	s_waitcnt lgkmcnt(3)
	v_pk_mul_f32 v[42:43], v[72:73], v[52:53] op_sel_hi:[1,0]
	v_pk_fma_f32 v[8:9], v[8:9], v[64:65], v[44:45] op_sel:[0,1,0] op_sel_hi:[1,1,1]
	v_pk_mul_f32 v[44:45], v[72:73], v[54:55] op_sel_hi:[1,0]
	v_pk_mul_f32 v[38:39], v[6:7], v[48:49] op_sel:[0,1] op_sel_hi:[1,1]
	v_pk_fma_f32 v[10:11], v[10:11], v[66:67], v[42:43] op_sel:[0,0,0] op_sel_hi:[1,0,1]
	s_waitcnt lgkmcnt(1)
	v_pk_mul_f32 v[42:43], v[72:73], v[56:57] op_sel_hi:[1,0]
	v_pk_fma_f32 v[38:39], v[8:9], v[50:51], v[38:39] op_sel:[0,1,0] op_sel_hi:[1,1,1]
	v_pk_fma_f32 v[12:13], v[12:13], v[66:67], v[44:45] op_sel:[0,1,0] op_sel_hi:[1,1,1]
	v_pk_mul_f32 v[44:45], v[72:73], v[58:59] op_sel_hi:[1,0]
	v_pk_fma_f32 v[38:39], v[10:11], v[52:53], v[38:39] op_sel:[0,1,0] op_sel_hi:[1,1,1]
	v_pk_fma_f32 v[14:15], v[14:15], v[68:69], v[42:43] op_sel:[0,0,0] op_sel_hi:[1,0,1]
	s_waitcnt lgkmcnt(0)
	v_pk_mul_f32 v[42:43], v[72:73], v[60:61] op_sel_hi:[1,0]
	v_pk_fma_f32 v[38:39], v[12:13], v[54:55], v[38:39] op_sel:[0,1,0] op_sel_hi:[1,1,1]
	v_pk_fma_f32 v[16:17], v[16:17], v[68:69], v[44:45] op_sel:[0,1,0] op_sel_hi:[1,1,1]
	v_pk_mul_f32 v[44:45], v[72:73], v[62:63] op_sel_hi:[1,0]
	v_pk_fma_f32 v[38:39], v[14:15], v[56:57], v[38:39] op_sel:[0,1,0] op_sel_hi:[1,1,1]
	v_pk_fma_f32 v[18:19], v[18:19], v[70:71], v[42:43] op_sel:[0,0,0] op_sel_hi:[1,0,1]
	v_pk_fma_f32 v[38:39], v[16:17], v[58:59], v[38:39] op_sel:[0,1,0] op_sel_hi:[1,1,1]
	v_pk_fma_f32 v[20:21], v[20:21], v[70:71], v[44:45] op_sel:[0,1,0] op_sel_hi:[1,1,1]
	v_pk_fma_f32 v[38:39], v[18:19], v[60:61], v[38:39] op_sel:[0,1,0] op_sel_hi:[1,1,1]
	v_pk_fma_f32 v[38:39], v[20:21], v[62:63], v[38:39] op_sel:[0,1,0] op_sel_hi:[1,1,1]
	s_add_u32 s14, s14, 0x1000
	s_addc_u32 s15, s15, 0
	v_add_f32_dpp v38, v38, v38 row_ror:8 row_mask:0xf bank_mask:0x3 bound_ctrl:1
	v_add_f32_dpp v38, v39, v39 row_ror:8 row_mask:0xf bank_mask:0xc bound_ctrl:1
	ds_read_b64 v[104:105], v23 offset:38400
	ds_read_b128 v[80:83], v2 offset:54528
	v_add_f32_dpp v38, v38, v38 row_half_mirror row_mask:0xf bank_mask:0xf bound_ctrl:1
	ds_read_b128 v[96:99], v22 offset:35584
	ds_read_b128 v[84:87], v2 offset:54784
	v_add_f32_dpp v38, v38, v38 quad_perm:[1,0,3,2] row_mask:0xf bank_mask:0xf bound_ctrl:1
	ds_read_b128 v[88:91], v2 offset:55040
	ds_read_b128 v[100:103], v22 offset:35840
	v_add_f32_dpp v38, v38, v38 quad_perm:[2,3,0,1] row_mask:0xf bank_mask:0xf bound_ctrl:1
	ds_read_b128 v[92:95], v2 offset:55296
	v_cvt_pk_bf16_f32 v47, v38, v38
	s_mov_b64 exec, s[2:3]
	global_store_short v28, v47, s[14:15] offset:-4096
	s_mov_b64 exec, -1
	s_waitcnt lgkmcnt(4)
	v_pk_mul_f32 v[42:43], v[104:105], v[80:81] op_sel_hi:[1,0]
	v_pk_mul_f32 v[44:45], v[104:105], v[82:83] op_sel_hi:[1,0]
	v_pk_fma_f32 v[6:7], v[6:7], v[96:97], v[42:43] op_sel:[0,0,0] op_sel_hi:[1,0,1]
	s_waitcnt lgkmcnt(3)
	v_pk_mul_f32 v[42:43], v[104:105], v[84:85] op_sel_hi:[1,0]
	v_pk_fma_f32 v[8:9], v[8:9], v[96:97], v[44:45] op_sel:[0,1,0] op_sel_hi:[1,1,1]
	v_pk_mul_f32 v[44:45], v[104:105], v[86:87] op_sel_hi:[1,0]
	v_pk_mul_f32 v[38:39], v[6:7], v[80:81] op_sel:[0,1] op_sel_hi:[1,1]
	v_pk_fma_f32 v[10:11], v[10:11], v[98:99], v[42:43] op_sel:[0,0,0] op_sel_hi:[1,0,1]
	s_waitcnt lgkmcnt(1)
	v_pk_mul_f32 v[42:43], v[104:105], v[88:89] op_sel_hi:[1,0]
	v_pk_fma_f32 v[38:39], v[8:9], v[82:83], v[38:39] op_sel:[0,1,0] op_sel_hi:[1,1,1]
	v_pk_fma_f32 v[12:13], v[12:13], v[98:99], v[44:45] op_sel:[0,1,0] op_sel_hi:[1,1,1]
	v_pk_mul_f32 v[44:45], v[104:105], v[90:91] op_sel_hi:[1,0]
	v_pk_fma_f32 v[38:39], v[10:11], v[84:85], v[38:39] op_sel:[0,1,0] op_sel_hi:[1,1,1]
	v_pk_fma_f32 v[14:15], v[14:15], v[100:101], v[42:43] op_sel:[0,0,0] op_sel_hi:[1,0,1]
	s_waitcnt lgkmcnt(0)
	v_pk_mul_f32 v[42:43], v[104:105], v[92:93] op_sel_hi:[1,0]
	v_pk_fma_f32 v[38:39], v[12:13], v[86:87], v[38:39] op_sel:[0,1,0] op_sel_hi:[1,1,1]
	v_pk_fma_f32 v[16:17], v[16:17], v[100:101], v[44:45] op_sel:[0,1,0] op_sel_hi:[1,1,1]
	v_pk_mul_f32 v[44:45], v[104:105], v[94:95] op_sel_hi:[1,0]
	v_pk_fma_f32 v[38:39], v[14:15], v[88:89], v[38:39] op_sel:[0,1,0] op_sel_hi:[1,1,1]
	v_pk_fma_f32 v[18:19], v[18:19], v[102:103], v[42:43] op_sel:[0,0,0] op_sel_hi:[1,0,1]
	v_pk_fma_f32 v[38:39], v[16:17], v[90:91], v[38:39] op_sel:[0,1,0] op_sel_hi:[1,1,1]
	v_pk_fma_f32 v[20:21], v[20:21], v[102:103], v[44:45] op_sel:[0,1,0] op_sel_hi:[1,1,1]
	v_pk_fma_f32 v[38:39], v[18:19], v[92:93], v[38:39] op_sel:[0,1,0] op_sel_hi:[1,1,1]
	v_pk_fma_f32 v[38:39], v[20:21], v[94:95], v[38:39] op_sel:[0,1,0] op_sel_hi:[1,1,1]
	s_add_u32 s14, s14, 0x1000
	s_addc_u32 s15, s15, 0
	v_add_f32_dpp v38, v38, v38 row_ror:8 row_mask:0xf bank_mask:0x3 bound_ctrl:1
	v_add_f32_dpp v38, v39, v39 row_ror:8 row_mask:0xf bank_mask:0xc bound_ctrl:1
	ds_read_b64 v[72:73], v23 offset:38656
	ds_read_b128 v[48:51], v2 offset:55552
	v_add_f32_dpp v38, v38, v38 row_half_mirror row_mask:0xf bank_mask:0xf bound_ctrl:1
	ds_read_b128 v[64:67], v22 offset:36096
	ds_read_b128 v[52:55], v2 offset:55808
	v_add_f32_dpp v38, v38, v38 quad_perm:[1,0,3,2] row_mask:0xf bank_mask:0xf bound_ctrl:1
	ds_read_b128 v[56:59], v2 offset:56064
	ds_read_b128 v[68:71], v22 offset:36352
	v_add_f32_dpp v38, v38, v38 quad_perm:[2,3,0,1] row_mask:0xf bank_mask:0xf bound_ctrl:1
	ds_read_b128 v[60:63], v2 offset:56320
	v_cvt_pk_bf16_f32 v47, v38, v38
	s_mov_b64 exec, s[2:3]
	global_store_short v28, v47, s[14:15] offset:-4096
	s_mov_b64 exec, -1
	s_waitcnt lgkmcnt(4)
	v_pk_mul_f32 v[42:43], v[72:73], v[48:49] op_sel_hi:[1,0]
	v_pk_mul_f32 v[44:45], v[72:73], v[50:51] op_sel_hi:[1,0]
	v_pk_fma_f32 v[6:7], v[6:7], v[64:65], v[42:43] op_sel:[0,0,0] op_sel_hi:[1,0,1]
	s_waitcnt lgkmcnt(3)
	v_pk_mul_f32 v[42:43], v[72:73], v[52:53] op_sel_hi:[1,0]
	v_pk_fma_f32 v[8:9], v[8:9], v[64:65], v[44:45] op_sel:[0,1,0] op_sel_hi:[1,1,1]
	v_pk_mul_f32 v[44:45], v[72:73], v[54:55] op_sel_hi:[1,0]
	v_pk_mul_f32 v[38:39], v[6:7], v[48:49] op_sel:[0,1] op_sel_hi:[1,1]
	v_pk_fma_f32 v[10:11], v[10:11], v[66:67], v[42:43] op_sel:[0,0,0] op_sel_hi:[1,0,1]
	s_waitcnt lgkmcnt(1)
	v_pk_mul_f32 v[42:43], v[72:73], v[56:57] op_sel_hi:[1,0]
	v_pk_fma_f32 v[38:39], v[8:9], v[50:51], v[38:39] op_sel:[0,1,0] op_sel_hi:[1,1,1]
	v_pk_fma_f32 v[12:13], v[12:13], v[66:67], v[44:45] op_sel:[0,1,0] op_sel_hi:[1,1,1]
	v_pk_mul_f32 v[44:45], v[72:73], v[58:59] op_sel_hi:[1,0]
	v_pk_fma_f32 v[38:39], v[10:11], v[52:53], v[38:39] op_sel:[0,1,0] op_sel_hi:[1,1,1]
	v_pk_fma_f32 v[14:15], v[14:15], v[68:69], v[42:43] op_sel:[0,0,0] op_sel_hi:[1,0,1]
	s_waitcnt lgkmcnt(0)
	v_pk_mul_f32 v[42:43], v[72:73], v[60:61] op_sel_hi:[1,0]
	v_pk_fma_f32 v[38:39], v[12:13], v[54:55], v[38:39] op_sel:[0,1,0] op_sel_hi:[1,1,1]
	v_pk_fma_f32 v[16:17], v[16:17], v[68:69], v[44:45] op_sel:[0,1,0] op_sel_hi:[1,1,1]
	v_pk_mul_f32 v[44:45], v[72:73], v[62:63] op_sel_hi:[1,0]
	v_pk_fma_f32 v[38:39], v[14:15], v[56:57], v[38:39] op_sel:[0,1,0] op_sel_hi:[1,1,1]
	v_pk_fma_f32 v[18:19], v[18:19], v[70:71], v[42:43] op_sel:[0,0,0] op_sel_hi:[1,0,1]
	v_pk_fma_f32 v[38:39], v[16:17], v[58:59], v[38:39] op_sel:[0,1,0] op_sel_hi:[1,1,1]
	v_pk_fma_f32 v[20:21], v[20:21], v[70:71], v[44:45] op_sel:[0,1,0] op_sel_hi:[1,1,1]
	v_pk_fma_f32 v[38:39], v[18:19], v[60:61], v[38:39] op_sel:[0,1,0] op_sel_hi:[1,1,1]
	v_pk_fma_f32 v[38:39], v[20:21], v[62:63], v[38:39] op_sel:[0,1,0] op_sel_hi:[1,1,1]
	s_add_u32 s14, s14, 0x1000
	s_addc_u32 s15, s15, 0
	v_add_f32_dpp v38, v38, v38 row_ror:8 row_mask:0xf bank_mask:0x3 bound_ctrl:1
	v_add_f32_dpp v38, v39, v39 row_ror:8 row_mask:0xf bank_mask:0xc bound_ctrl:1
	ds_read_b64 v[104:105], v23 offset:38912
	ds_read_b128 v[80:83], v2 offset:56576
	v_add_f32_dpp v38, v38, v38 row_half_mirror row_mask:0xf bank_mask:0xf bound_ctrl:1
	ds_read_b128 v[96:99], v22 offset:36608
	ds_read_b128 v[84:87], v2 offset:56832
	v_add_f32_dpp v38, v38, v38 quad_perm:[1,0,3,2] row_mask:0xf bank_mask:0xf bound_ctrl:1
	ds_read_b128 v[88:91], v2 offset:57088
	ds_read_b128 v[100:103], v22 offset:36864
	v_add_f32_dpp v38, v38, v38 quad_perm:[2,3,0,1] row_mask:0xf bank_mask:0xf bound_ctrl:1
	ds_read_b128 v[92:95], v2 offset:57344
	v_cvt_pk_bf16_f32 v47, v38, v38
	s_mov_b64 exec, s[2:3]
	global_store_short v28, v47, s[14:15] offset:-4096
	s_mov_b64 exec, -1
	s_waitcnt lgkmcnt(4)
	v_pk_mul_f32 v[42:43], v[104:105], v[80:81] op_sel_hi:[1,0]
	v_pk_mul_f32 v[44:45], v[104:105], v[82:83] op_sel_hi:[1,0]
	v_pk_fma_f32 v[6:7], v[6:7], v[96:97], v[42:43] op_sel:[0,0,0] op_sel_hi:[1,0,1]
	s_waitcnt lgkmcnt(3)
	v_pk_mul_f32 v[42:43], v[104:105], v[84:85] op_sel_hi:[1,0]
	v_pk_fma_f32 v[8:9], v[8:9], v[96:97], v[44:45] op_sel:[0,1,0] op_sel_hi:[1,1,1]
	v_pk_mul_f32 v[44:45], v[104:105], v[86:87] op_sel_hi:[1,0]
	v_pk_mul_f32 v[38:39], v[6:7], v[80:81] op_sel:[0,1] op_sel_hi:[1,1]
	v_pk_fma_f32 v[10:11], v[10:11], v[98:99], v[42:43] op_sel:[0,0,0] op_sel_hi:[1,0,1]
	s_waitcnt lgkmcnt(1)
	v_pk_mul_f32 v[42:43], v[104:105], v[88:89] op_sel_hi:[1,0]
	v_pk_fma_f32 v[38:39], v[8:9], v[82:83], v[38:39] op_sel:[0,1,0] op_sel_hi:[1,1,1]
	v_pk_fma_f32 v[12:13], v[12:13], v[98:99], v[44:45] op_sel:[0,1,0] op_sel_hi:[1,1,1]
	v_pk_mul_f32 v[44:45], v[104:105], v[90:91] op_sel_hi:[1,0]
	v_pk_fma_f32 v[38:39], v[10:11], v[84:85], v[38:39] op_sel:[0,1,0] op_sel_hi:[1,1,1]
	v_pk_fma_f32 v[14:15], v[14:15], v[100:101], v[42:43] op_sel:[0,0,0] op_sel_hi:[1,0,1]
	s_waitcnt lgkmcnt(0)
	v_pk_mul_f32 v[42:43], v[104:105], v[92:93] op_sel_hi:[1,0]
	v_pk_fma_f32 v[38:39], v[12:13], v[86:87], v[38:39] op_sel:[0,1,0] op_sel_hi:[1,1,1]
	v_pk_fma_f32 v[16:17], v[16:17], v[100:101], v[44:45] op_sel:[0,1,0] op_sel_hi:[1,1,1]
	v_pk_mul_f32 v[44:45], v[104:105], v[94:95] op_sel_hi:[1,0]
	v_pk_fma_f32 v[38:39], v[14:15], v[88:89], v[38:39] op_sel:[0,1,0] op_sel_hi:[1,1,1]
	v_pk_fma_f32 v[18:19], v[18:19], v[102:103], v[42:43] op_sel:[0,0,0] op_sel_hi:[1,0,1]
	v_pk_fma_f32 v[38:39], v[16:17], v[90:91], v[38:39] op_sel:[0,1,0] op_sel_hi:[1,1,1]
	v_pk_fma_f32 v[20:21], v[20:21], v[102:103], v[44:45] op_sel:[0,1,0] op_sel_hi:[1,1,1]
	v_pk_fma_f32 v[38:39], v[18:19], v[92:93], v[38:39] op_sel:[0,1,0] op_sel_hi:[1,1,1]
	v_pk_fma_f32 v[38:39], v[20:21], v[94:95], v[38:39] op_sel:[0,1,0] op_sel_hi:[1,1,1]
	s_add_u32 s14, s14, 0x1000
	s_addc_u32 s15, s15, 0
	v_add_f32_dpp v38, v38, v38 row_ror:8 row_mask:0xf bank_mask:0x3 bound_ctrl:1
	v_add_f32_dpp v38, v39, v39 row_ror:8 row_mask:0xf bank_mask:0xc bound_ctrl:1
	ds_read_b64 v[72:73], v3 offset:20736
	ds_read_b128 v[48:51], v2 offset:256
	v_add_f32_dpp v38, v38, v38 row_half_mirror row_mask:0xf bank_mask:0xf bound_ctrl:1
	ds_read_b128 v[64:67], v2 offset:16640
	ds_read_b128 v[52:55], v2 offset:512
	v_add_f32_dpp v38, v38, v38 quad_perm:[1,0,3,2] row_mask:0xf bank_mask:0xf bound_ctrl:1
	ds_read_b128 v[56:59], v2 offset:768
	ds_read_b128 v[68:71], v2 offset:16896
	v_add_f32_dpp v38, v38, v38 quad_perm:[2,3,0,1] row_mask:0xf bank_mask:0xf bound_ctrl:1
	ds_read_b128 v[60:63], v2 offset:1024
	v_cvt_pk_bf16_f32 v47, v38, v38
	s_mov_b64 exec, s[2:3]
	global_store_short v28, v47, s[14:15] offset:-4096
	s_mov_b64 exec, -1
	s_waitcnt vmcnt(8)
	v_lshlrev_b32_e32 v144, 16, v110
	v_lshlrev_b32_e32 v145, 16, v111
	v_and_b32_e32 v146, s17, v110
	v_and_b32_e32 v147, s17, v111
	v_lshlrev_b32_e32 v148, 16, v112
	v_lshlrev_b32_e32 v149, 16, v113
	v_and_b32_e32 v150, s17, v112
	v_and_b32_e32 v151, s17, v113
	v_lshlrev_b32_e32 v152, 16, v114
	v_and_b32_e32 v153, s17, v114
	v_rcp_f32_e32 v25, v24
	v_mul_f32_e32 v149, v24, v149
	v_mul_f32_e32 v151, v24, v151
	v_mul_f32_e32 v145, 0x3db504f3, v145
	v_mul_f32_e32 v147, 0x3db504f3, v147
	v_cndmask_b32_e64 v27, 1.0, v25, s[20:21]
	v_mul_f32_e32 v24, v24, v26
	v_mul_f32_e32 v152, v27, v152
	v_mul_f32_e32 v153, v27, v153
	ds_write_b128 v29, v[144:147] offset:24832
	ds_write_b128 v29, v[148:151] offset:33024
	ds_write_b64 v30, v[116:117] offset:24832
	ds_write_b64 v31, v[152:153] offset:24832
	s_add_i32 s16, s16, 8
	s_waitcnt lgkmcnt(0)
	s_barrier
	s_cmpk_lt_u32 s16, 0x800
	s_cbranch_scc1 .Lgla2_loop
